# K-loop LDS-DMA split 3/5/3/5 per load segment (one piece of each A half-0 stage moved one phase later; waits 8/7/8/7)
# baseline (speedup 1.0000x reference)
; #define PG8_STAGE(bufoff, gbase, voff) do { _Pragma("unroll") for (int _i = 0; _i < 2; ++_i) \
;         __builtin_amdgcn_global_load_lds((const unsigned*)((const char*)(gbase) + (voff)[_i]), (LAS unsigned*)(lds + (bufoff) + ldsw + _i * 8192), 16, 0, 0); } while (0)
; #define PG8_LDA(dst, b, h) do { _Pragma("unroll") for (int m = 0; m < 4; ++m) _Pragma("unroll") for (int k = 0; k < 2; ++k) dst[m][k] = *(const LAS bf16x8*)(lds + PG8_SA(b, h) + aoff + m * 2048 + k * 1024); } while (0)
; #define PG8_LDB(dst, b, h) do { _Pragma("unroll") for (int n = 0; n < 2; ++n) _Pragma("unroll") for (int k = 0; k < 2; ++k) dst[n][k] = *(const LAS bf16x8*)(lds + PG8_SB(b, h) + boff + n * 2048 + k * 1024); } while (0)
; #define PG8_MMA(ai, bj, At, Bt) do { __builtin_amdgcn_s_setprio(1); _Pragma("unroll") for (int m = 0; m < 4; ++m) _Pragma("unroll") for (int n = 0; n < 2; ++n) _Pragma("unroll") for (int k = 0; k < 2; ++k) \
;         acc[ai][bj][m][n] = __builtin_amdgcn_mfma_f32_16x16x32_bf16(Bt[n][k], At[m][k], acc[ai][bj][m][n], 0, 0, 0); __builtin_amdgcn_s_setprio(0); } while (0)
; #define PG8_WAIT_V(n) asm volatile("s_waitcnt vmcnt(" #n ")" ::: "memory")
; #define PG8_WAIT_L(n) asm volatile("s_waitcnt lgkmcnt(" #n ")" ::: "memory")
; #define PG8_BAR __builtin_amdgcn_s_barrier()
; #define PG8_SCHED __builtin_amdgcn_sched_barrier(0)
; template <class Epi, class Sched, bool ALIGN_EPI = false, bool SP2 = false>
; __device__ __forceinline__ void gemm_phase(LAS unsigned char* lds, const Gemm g, const Sched& S, const Epi& E) {
;     ...
;             PG8_LDB(B0, 0, 0); PG8_LDB(B1, 0, 1); PG8_SCHED; PG8_LDA(At, 0, 0); PG8_STAGE(PG8_SA(1, 1), a1 + hstep, voffA);
;             PG8_WAIT_V(8); PG8_WAIT_L(0); PG8_BAR; PG8_MMA(0, 0, At, B0); PG8_MMA(0, 1, At, B1); PG8_BAR; PG8_SCHED;
;             PG8_LDA(At, 0, 1); PG8_STAGE(PG8_SB(0, 0), b2, voffB); PG8_STAGE(PG8_SB(0, 1), b2 + hstep, voffB); PG8_STAGE(PG8_SA(0, 0), a2, voffA);
.LBB0_260:
	s_add_u32 s100, s10, 0xfff00000
	s_addc_u32 s101, s11, -1
	s_add_u32 s12, s10, 0xfff00080
	s_addc_u32 s13, s11, -1
	s_add_i32 s44, 0, 0x10000
	s_cmp_eq_u32 s42, 60
	s_cselect_b32 s15, s2, s13
	s_cselect_b32 s14, s3, s12
	v_add_u32_e32 v146, s44, v149
	s_cselect_b32 s13, s17, s41
	s_cselect_b32 s12, s23, s25
	s_add_i32 s48, 0, 0x14000
	ds_read_b128 v[142:145], v146
	ds_read_b128 v[156:159], v146 offset:1024
	ds_read_b128 v[160:163], v146 offset:2048
	ds_read_b128 v[164:167], v146 offset:3072
	v_add_u32_e32 v146, s48, v149
	ds_read_b128 v[168:171], v146
	ds_read_b128 v[172:175], v146 offset:1024
	ds_read_b128 v[176:179], v146 offset:2048
	ds_read_b128 v[180:183], v146 offset:3072
	s_add_i32 m0, s34, 0xc000
	ds_read_b128 v[184:187], v155
	ds_read_b128 v[188:191], v155 offset:1024
	ds_read_b128 v[198:201], v155 offset:2048
	ds_read_b128 v[202:205], v155 offset:3072
	ds_read_b128 v[206:209], v155 offset:4096
	ds_read_b128 v[210:213], v155 offset:5120
	ds_read_b128 v[214:217], v155 offset:6144
	ds_read_b128 v[228:231], v155 offset:7168
	s_mov_b32 m0, s39
	s_nop 0
	global_load_lds_dwordx4 v130, s[100:101]
	s_add_i32 m0, s34, 0xc000
	s_nop 0
	global_load_lds_dwordx4 v138, s[10:11]
	s_add_i32 m0, s34, 0xe000
	s_nop 0
	global_load_lds_dwordx4 v140, s[10:11]
	s_waitcnt vmcnt(8)
	s_waitcnt lgkmcnt(0)
	s_barrier
	s_setprio 1
	s_waitcnt lgkmcnt(0)
	v_mfma_f32_16x16x32_bf16 v[124:127], v[142:145], v[184:187], v[124:127]
	v_mfma_f32_16x16x32_bf16 v[120:123], v[160:163], v[184:187], v[120:123]
	v_mfma_f32_16x16x32_bf16 v[108:111], v[142:145], v[198:201], v[108:111]
	v_mfma_f32_16x16x32_bf16 v[104:107], v[160:163], v[198:201], v[104:107]
	v_mfma_f32_16x16x32_bf16 v[92:95], v[142:145], v[206:209], v[92:95]
	v_mfma_f32_16x16x32_bf16 v[88:91], v[160:163], v[206:209], v[88:91]
	v_mfma_f32_16x16x32_bf16 v[76:79], v[142:145], v[214:217], v[76:79]
	v_mfma_f32_16x16x32_bf16 v[72:75], v[160:163], v[214:217], v[72:75]
	v_mfma_f32_16x16x32_bf16 v[124:127], v[156:159], v[188:191], v[124:127]
	v_mfma_f32_16x16x32_bf16 v[120:123], v[164:167], v[188:191], v[120:123]
	v_mfma_f32_16x16x32_bf16 v[108:111], v[156:159], v[202:205], v[108:111]
	v_mfma_f32_16x16x32_bf16 v[104:107], v[164:167], v[202:205], v[104:107]
	v_mfma_f32_16x16x32_bf16 v[92:95], v[156:159], v[210:213], v[92:95]
	v_mfma_f32_16x16x32_bf16 v[88:91], v[164:167], v[210:213], v[88:91]
	v_mfma_f32_16x16x32_bf16 v[76:79], v[156:159], v[228:231], v[76:79]
	v_mfma_f32_16x16x32_bf16 v[72:75], v[164:167], v[228:231], v[72:75]
	s_setprio 0
	s_setprio 1
	v_mfma_f32_16x16x32_bf16 v[116:119], v[168:171], v[184:187], v[116:119]
	v_mfma_f32_16x16x32_bf16 v[112:115], v[176:179], v[184:187], v[112:115]
	v_mfma_f32_16x16x32_bf16 v[100:103], v[168:171], v[198:201], v[100:103]
	v_mfma_f32_16x16x32_bf16 v[96:99], v[176:179], v[198:201], v[96:99]
	v_mfma_f32_16x16x32_bf16 v[84:87], v[168:171], v[206:209], v[84:87]
	v_mfma_f32_16x16x32_bf16 v[80:83], v[176:179], v[206:209], v[80:83]
	v_mfma_f32_16x16x32_bf16 v[68:71], v[168:171], v[214:217], v[68:71]
	v_mfma_f32_16x16x32_bf16 v[64:67], v[176:179], v[214:217], v[64:67]
	v_mfma_f32_16x16x32_bf16 v[116:119], v[172:175], v[188:191], v[116:119]
	v_mfma_f32_16x16x32_bf16 v[112:115], v[180:183], v[188:191], v[112:115]
	v_mfma_f32_16x16x32_bf16 v[100:103], v[172:175], v[202:205], v[100:103]
	v_mfma_f32_16x16x32_bf16 v[96:99], v[180:183], v[202:205], v[96:99]
	v_mfma_f32_16x16x32_bf16 v[84:87], v[172:175], v[210:213], v[84:87]
	v_mfma_f32_16x16x32_bf16 v[80:83], v[180:183], v[210:213], v[80:83]
	v_mfma_f32_16x16x32_bf16 v[68:71], v[172:175], v[228:231], v[68:71]
	v_mfma_f32_16x16x32_bf16 v[64:67], v[180:183], v[228:231], v[64:67]
	s_setprio 0
	s_barrier
	s_add_u32 s98, s12, 0x80
	s_addc_u32 s99, s13, 0
	s_add_u32 s100, s14, 0x80
	s_addc_u32 s101, s15, 0
	s_add_i32 s44, s44, s7
	s_mov_b32 m0, s44
	ds_read_b128 v[184:187], v155 offset:16384
	ds_read_b128 v[188:191], v155 offset:17408
	ds_read_b128 v[198:201], v155 offset:18432
	ds_read_b128 v[202:205], v155 offset:19456
	ds_read_b128 v[206:209], v155 offset:20480
	ds_read_b128 v[210:213], v155 offset:21504
	ds_read_b128 v[214:217], v155 offset:22528
	ds_read_b128 v[228:231], v155 offset:23552
	global_load_lds_dwordx4 v196, s[12:13]
	s_add_i32 m0, s44, 0x2000
	s_add_u32 s46, s12, 0x100000
	s_addc_u32 s47, s13, 0
	s_add_i32 s44, s48, s7
	global_load_lds_dwordx4 v128, s[12:13]
	s_mov_b32 m0, s44
	s_nop 0
	global_load_lds_dwordx4 v196, s[46:47]
	s_add_i32 m0, s44, 0x2000
	s_nop 0
	global_load_lds_dwordx4 v128, s[46:47]
	s_mov_b32 m0, s34
	s_nop 0
	global_load_lds_dwordx4 v132, s[14:15]
	s_waitcnt vmcnt(7)
	s_waitcnt lgkmcnt(0)
	s_barrier
; #define PG8_STAGE(bufoff, gbase, voff) do { _Pragma("unroll") for (int _i = 0; _i < 2; ++_i) \
;         __builtin_amdgcn_global_load_lds((const unsigned*)((const char*)(gbase) + (voff)[_i]), (LAS unsigned*)(lds + (bufoff) + ldsw + _i * 8192), 16, 0, 0); } while (0)
; #define PG8_LDA(dst, b, h) do { _Pragma("unroll") for (int m = 0; m < 4; ++m) _Pragma("unroll") for (int k = 0; k < 2; ++k) dst[m][k] = *(const LAS bf16x8*)(lds + PG8_SA(b, h) + aoff + m * 2048 + k * 1024); } while (0)
; #define PG8_LDB(dst, b, h) do { _Pragma("unroll") for (int n = 0; n < 2; ++n) _Pragma("unroll") for (int k = 0; k < 2; ++k) dst[n][k] = *(const LAS bf16x8*)(lds + PG8_SB(b, h) + boff + n * 2048 + k * 1024); } while (0)
; #define PG8_MMA(ai, bj, At, Bt) do { __builtin_amdgcn_s_setprio(1); _Pragma("unroll") for (int m = 0; m < 4; ++m) _Pragma("unroll") for (int n = 0; n < 2; ++n) _Pragma("unroll") for (int k = 0; k < 2; ++k) \
;         acc[ai][bj][m][n] = __builtin_amdgcn_mfma_f32_16x16x32_bf16(Bt[n][k], At[m][k], acc[ai][bj][m][n], 0, 0, 0); __builtin_amdgcn_s_setprio(0); } while (0)
; #define PG8_WAIT_V(n) asm volatile("s_waitcnt vmcnt(" #n ")" ::: "memory")
; #define PG8_WAIT_L(n) asm volatile("s_waitcnt lgkmcnt(" #n ")" ::: "memory")
; #define PG8_BAR __builtin_amdgcn_s_barrier()
; #define PG8_SCHED __builtin_amdgcn_sched_barrier(0)
; template <class Epi, class Sched, bool ALIGN_EPI = false, bool SP2 = false>
; __device__ __forceinline__ void gemm_phase(LAS unsigned char* lds, const Gemm g, const Sched& S, const Epi& E) {
;     ...
;             PG8_WAIT_V(8); PG8_WAIT_L(0); PG8_BAR; PG8_MMA(1, 0, At, B0); PG8_MMA(1, 1, At, B1); PG8_BAR; PG8_SCHED;
;             PG8_LDB(B0, 1, 0); PG8_LDB(B1, 1, 1); PG8_SCHED; PG8_LDA(At, 1, 0); PG8_STAGE(PG8_SA(0, 1), a2 + hstep, voffA);
	s_setprio 1
	s_waitcnt lgkmcnt(0)
	v_mfma_f32_16x16x32_bf16 v[60:63], v[142:145], v[184:187], v[60:63]
	v_mfma_f32_16x16x32_bf16 v[56:59], v[160:163], v[184:187], v[56:59]
	v_mfma_f32_16x16x32_bf16 v[44:47], v[142:145], v[198:201], v[44:47]
	v_mfma_f32_16x16x32_bf16 v[40:43], v[160:163], v[198:201], v[40:43]
	v_mfma_f32_16x16x32_bf16 v[28:31], v[142:145], v[206:209], v[28:31]
	v_mfma_f32_16x16x32_bf16 v[24:27], v[160:163], v[206:209], v[24:27]
	v_mfma_f32_16x16x32_bf16 v[12:15], v[142:145], v[214:217], v[12:15]
	v_mfma_f32_16x16x32_bf16 v[8:11], v[160:163], v[214:217], v[8:11]
	v_mfma_f32_16x16x32_bf16 v[60:63], v[156:159], v[188:191], v[60:63]
	v_mfma_f32_16x16x32_bf16 v[56:59], v[164:167], v[188:191], v[56:59]
	v_mfma_f32_16x16x32_bf16 v[44:47], v[156:159], v[202:205], v[44:47]
	v_mfma_f32_16x16x32_bf16 v[40:43], v[164:167], v[202:205], v[40:43]
	v_mfma_f32_16x16x32_bf16 v[28:31], v[156:159], v[210:213], v[28:31]
	v_mfma_f32_16x16x32_bf16 v[24:27], v[164:167], v[210:213], v[24:27]
	v_mfma_f32_16x16x32_bf16 v[12:15], v[156:159], v[228:231], v[12:15]
	v_mfma_f32_16x16x32_bf16 v[8:11], v[164:167], v[228:231], v[8:11]
	s_setprio 0
	s_setprio 1
	v_mfma_f32_16x16x32_bf16 v[52:55], v[168:171], v[184:187], v[52:55]
	v_mfma_f32_16x16x32_bf16 v[48:51], v[176:179], v[184:187], v[48:51]
	v_mfma_f32_16x16x32_bf16 v[36:39], v[168:171], v[198:201], v[36:39]
	v_mfma_f32_16x16x32_bf16 v[32:35], v[176:179], v[198:201], v[32:35]
	v_mfma_f32_16x16x32_bf16 v[20:23], v[168:171], v[206:209], v[20:23]
	v_mfma_f32_16x16x32_bf16 v[16:19], v[176:179], v[206:209], v[16:19]
	v_mfma_f32_16x16x32_bf16 v[4:7], v[168:171], v[214:217], v[4:7]
	v_mfma_f32_16x16x32_bf16 v[0:3], v[176:179], v[214:217], v[0:3]
	v_mfma_f32_16x16x32_bf16 v[52:55], v[172:175], v[188:191], v[52:55]
	v_mfma_f32_16x16x32_bf16 v[48:51], v[180:183], v[188:191], v[48:51]
	v_mfma_f32_16x16x32_bf16 v[36:39], v[172:175], v[202:205], v[36:39]
	v_mfma_f32_16x16x32_bf16 v[32:35], v[180:183], v[202:205], v[32:35]
	v_mfma_f32_16x16x32_bf16 v[20:23], v[172:175], v[210:213], v[20:23]
	v_mfma_f32_16x16x32_bf16 v[16:19], v[180:183], v[210:213], v[16:19]
	v_mfma_f32_16x16x32_bf16 v[4:7], v[172:175], v[228:231], v[4:7]
	v_mfma_f32_16x16x32_bf16 v[0:3], v[180:183], v[228:231], v[0:3]
	s_setprio 0
	s_barrier
	s_add_i32 s44, 0, 0x18000
	s_add_i32 s46, 0, 0x1c000
	v_add_u32_e32 v164, s44, v149
	v_add_u32_e32 v180, s46, v149
	ds_read_b128 v[142:145], v164
	ds_read_b128 v[156:159], v164 offset:1024
	ds_read_b128 v[160:163], v164 offset:2048
	ds_read_b128 v[164:167], v164 offset:3072
	ds_read_b128 v[168:171], v180
	ds_read_b128 v[172:175], v180 offset:1024
	ds_read_b128 v[176:179], v180 offset:2048
	ds_read_b128 v[180:183], v180 offset:3072
	s_mov_b32 m0, s35
	s_nop 0
	global_load_lds_dwordx4 v130, s[14:15]
	s_add_u32 s14, s14, 0x100000
	s_addc_u32 s15, s15, 0
	s_mov_b32 m0, s36
	ds_read_b128 v[184:187], v155 offset:32768
	ds_read_b128 v[188:191], v155 offset:33792
	ds_read_b128 v[198:201], v155 offset:34816
	ds_read_b128 v[202:205], v155 offset:35840
	ds_read_b128 v[206:209], v155 offset:36864
	ds_read_b128 v[210:213], v155 offset:37888
	ds_read_b128 v[214:217], v155 offset:38912
	ds_read_b128 v[228:231], v155 offset:39936
	global_load_lds_dwordx4 v132, s[14:15]
	s_mov_b32 m0, s37
	s_nop 0
	global_load_lds_dwordx4 v130, s[14:15]
	s_waitcnt vmcnt(8)
	s_waitcnt lgkmcnt(0)
	s_barrier
; #define PG8_STAGE(bufoff, gbase, voff) do { _Pragma("unroll") for (int _i = 0; _i < 2; ++_i) \
;         __builtin_amdgcn_global_load_lds((const unsigned*)((const char*)(gbase) + (voff)[_i]), (LAS unsigned*)(lds + (bufoff) + ldsw + _i * 8192), 16, 0, 0); } while (0)
; #define PG8_LDA(dst, b, h) do { _Pragma("unroll") for (int m = 0; m < 4; ++m) _Pragma("unroll") for (int k = 0; k < 2; ++k) dst[m][k] = *(const LAS bf16x8*)(lds + PG8_SA(b, h) + aoff + m * 2048 + k * 1024); } while (0)
; #define PG8_MMA(ai, bj, At, Bt) do { __builtin_amdgcn_s_setprio(1); _Pragma("unroll") for (int m = 0; m < 4; ++m) _Pragma("unroll") for (int n = 0; n < 2; ++n) _Pragma("unroll") for (int k = 0; k < 2; ++k) \
;         acc[ai][bj][m][n] = __builtin_amdgcn_mfma_f32_16x16x32_bf16(Bt[n][k], At[m][k], acc[ai][bj][m][n], 0, 0, 0); __builtin_amdgcn_s_setprio(0); } while (0)
; #define PG8_WAIT_V(n) asm volatile("s_waitcnt vmcnt(" #n ")" ::: "memory")
; #define PG8_WAIT_L(n) asm volatile("s_waitcnt lgkmcnt(" #n ")" ::: "memory")
; #define PG8_BAR __builtin_amdgcn_s_barrier()
; #define PG8_SCHED __builtin_amdgcn_sched_barrier(0)
; template <class Epi, class Sched, bool ALIGN_EPI = false, bool SP2 = false>
; __device__ __forceinline__ void gemm_phase(LAS unsigned char* lds, const Gemm g, const Sched& S, const Epi& E) {
;     ...
;             PG8_WAIT_V(8); PG8_WAIT_L(0); PG8_BAR; PG8_MMA(0, 0, At, B0); PG8_MMA(0, 1, At, B1); PG8_BAR; PG8_SCHED;
;             PG8_LDA(At, 1, 1); PG8_STAGE(PG8_SB(1, 0), b3, voffB); PG8_STAGE(PG8_SB(1, 1), b3 + hstep, voffB); PG8_STAGE(PG8_SA(1, 0), a3, voffA);
;             PG8_WAIT_V(8); PG8_WAIT_L(0); PG8_BAR; PG8_MMA(1, 0, At, B0); PG8_MMA(1, 1, At, B1); PG8_BAR; PG8_SCHED;
	s_setprio 1
	s_waitcnt lgkmcnt(0)
	v_mfma_f32_16x16x32_bf16 v[124:127], v[142:145], v[184:187], v[124:127]
	v_mfma_f32_16x16x32_bf16 v[120:123], v[160:163], v[184:187], v[120:123]
	v_mfma_f32_16x16x32_bf16 v[108:111], v[142:145], v[198:201], v[108:111]
	v_mfma_f32_16x16x32_bf16 v[104:107], v[160:163], v[198:201], v[104:107]
	v_mfma_f32_16x16x32_bf16 v[92:95], v[142:145], v[206:209], v[92:95]
	v_mfma_f32_16x16x32_bf16 v[88:91], v[160:163], v[206:209], v[88:91]
	v_mfma_f32_16x16x32_bf16 v[76:79], v[142:145], v[214:217], v[76:79]
	v_mfma_f32_16x16x32_bf16 v[72:75], v[160:163], v[214:217], v[72:75]
	v_mfma_f32_16x16x32_bf16 v[124:127], v[156:159], v[188:191], v[124:127]
	v_mfma_f32_16x16x32_bf16 v[120:123], v[164:167], v[188:191], v[120:123]
	v_mfma_f32_16x16x32_bf16 v[108:111], v[156:159], v[202:205], v[108:111]
	v_mfma_f32_16x16x32_bf16 v[104:107], v[164:167], v[202:205], v[104:107]
	v_mfma_f32_16x16x32_bf16 v[92:95], v[156:159], v[210:213], v[92:95]
	v_mfma_f32_16x16x32_bf16 v[88:91], v[164:167], v[210:213], v[88:91]
	v_mfma_f32_16x16x32_bf16 v[76:79], v[156:159], v[228:231], v[76:79]
	v_mfma_f32_16x16x32_bf16 v[72:75], v[164:167], v[228:231], v[72:75]
	s_setprio 0
	s_setprio 1
	v_mfma_f32_16x16x32_bf16 v[116:119], v[168:171], v[184:187], v[116:119]
	v_mfma_f32_16x16x32_bf16 v[112:115], v[176:179], v[184:187], v[112:115]
	v_mfma_f32_16x16x32_bf16 v[100:103], v[168:171], v[198:201], v[100:103]
	v_mfma_f32_16x16x32_bf16 v[96:99], v[176:179], v[198:201], v[96:99]
	v_mfma_f32_16x16x32_bf16 v[84:87], v[168:171], v[206:209], v[84:87]
	v_mfma_f32_16x16x32_bf16 v[80:83], v[176:179], v[206:209], v[80:83]
	v_mfma_f32_16x16x32_bf16 v[68:71], v[168:171], v[214:217], v[68:71]
	v_mfma_f32_16x16x32_bf16 v[64:67], v[176:179], v[214:217], v[64:67]
	v_mfma_f32_16x16x32_bf16 v[116:119], v[172:175], v[188:191], v[116:119]
	v_mfma_f32_16x16x32_bf16 v[112:115], v[180:183], v[188:191], v[112:115]
	v_mfma_f32_16x16x32_bf16 v[100:103], v[172:175], v[202:205], v[100:103]
	v_mfma_f32_16x16x32_bf16 v[96:99], v[180:183], v[202:205], v[96:99]
	v_mfma_f32_16x16x32_bf16 v[84:87], v[172:175], v[210:213], v[84:87]
	v_mfma_f32_16x16x32_bf16 v[80:83], v[180:183], v[210:213], v[80:83]
	v_mfma_f32_16x16x32_bf16 v[68:71], v[172:175], v[228:231], v[68:71]
	v_mfma_f32_16x16x32_bf16 v[64:67], v[180:183], v[228:231], v[64:67]
	s_setprio 0
	s_barrier
	s_add_i32 s14, s44, s7
	s_mov_b32 m0, s14
	ds_read_b128 v[184:187], v155 offset:49152
	ds_read_b128 v[188:191], v155 offset:50176
	ds_read_b128 v[198:201], v155 offset:51200
	ds_read_b128 v[202:205], v155 offset:52224
	ds_read_b128 v[206:209], v155 offset:53248
	ds_read_b128 v[210:213], v155 offset:54272
	ds_read_b128 v[214:217], v155 offset:55296
	ds_read_b128 v[228:231], v155 offset:56320
	global_load_lds_dwordx4 v196, s[98:99]
	s_add_i32 m0, s14, 0x2000
	s_add_u32 s12, s12, 0x100080
	s_addc_u32 s13, s13, 0
	s_add_i32 s14, s46, s7
	global_load_lds_dwordx4 v128, s[98:99]
	s_mov_b32 m0, s14
	s_nop 0
	global_load_lds_dwordx4 v196, s[12:13]
	s_add_i32 m0, s14, 0x2000
	s_nop 0
	global_load_lds_dwordx4 v128, s[12:13]
	s_mov_b32 m0, s38
	s_nop 0
	global_load_lds_dwordx4 v132, s[100:101]
	s_waitcnt vmcnt(7)
	s_waitcnt lgkmcnt(0)
	s_barrier
	s_setprio 1
	s_waitcnt lgkmcnt(0)
	v_mfma_f32_16x16x32_bf16 v[60:63], v[142:145], v[184:187], v[60:63]
	v_mfma_f32_16x16x32_bf16 v[56:59], v[160:163], v[184:187], v[56:59]
	v_mfma_f32_16x16x32_bf16 v[44:47], v[142:145], v[198:201], v[44:47]
	v_mfma_f32_16x16x32_bf16 v[40:43], v[160:163], v[198:201], v[40:43]
	v_mfma_f32_16x16x32_bf16 v[28:31], v[142:145], v[206:209], v[28:31]
	v_mfma_f32_16x16x32_bf16 v[24:27], v[160:163], v[206:209], v[24:27]
	v_mfma_f32_16x16x32_bf16 v[12:15], v[142:145], v[214:217], v[12:15]
	v_mfma_f32_16x16x32_bf16 v[8:11], v[160:163], v[214:217], v[8:11]
	v_mfma_f32_16x16x32_bf16 v[60:63], v[156:159], v[188:191], v[60:63]
	v_mfma_f32_16x16x32_bf16 v[56:59], v[164:167], v[188:191], v[56:59]
	v_mfma_f32_16x16x32_bf16 v[44:47], v[156:159], v[202:205], v[44:47]
	v_mfma_f32_16x16x32_bf16 v[40:43], v[164:167], v[202:205], v[40:43]
	v_mfma_f32_16x16x32_bf16 v[28:31], v[156:159], v[210:213], v[28:31]
	v_mfma_f32_16x16x32_bf16 v[24:27], v[164:167], v[210:213], v[24:27]
	v_mfma_f32_16x16x32_bf16 v[12:15], v[156:159], v[228:231], v[12:15]
	v_mfma_f32_16x16x32_bf16 v[8:11], v[164:167], v[228:231], v[8:11]
	s_setprio 0
	s_setprio 1
	v_mfma_f32_16x16x32_bf16 v[52:55], v[168:171], v[184:187], v[52:55]
	v_mfma_f32_16x16x32_bf16 v[48:51], v[176:179], v[184:187], v[48:51]
	v_mfma_f32_16x16x32_bf16 v[36:39], v[168:171], v[198:201], v[36:39]
	v_mfma_f32_16x16x32_bf16 v[32:35], v[176:179], v[198:201], v[32:35]
	v_mfma_f32_16x16x32_bf16 v[20:23], v[168:171], v[206:209], v[20:23]
	v_mfma_f32_16x16x32_bf16 v[16:19], v[176:179], v[206:209], v[16:19]
	v_mfma_f32_16x16x32_bf16 v[4:7], v[168:171], v[214:217], v[4:7]
	v_mfma_f32_16x16x32_bf16 v[0:3], v[176:179], v[214:217], v[0:3]
	v_mfma_f32_16x16x32_bf16 v[52:55], v[172:175], v[188:191], v[52:55]
	v_mfma_f32_16x16x32_bf16 v[48:51], v[180:183], v[188:191], v[48:51]
	v_mfma_f32_16x16x32_bf16 v[36:39], v[172:175], v[202:205], v[36:39]
	v_mfma_f32_16x16x32_bf16 v[32:35], v[180:183], v[202:205], v[32:35]
	v_mfma_f32_16x16x32_bf16 v[20:23], v[172:175], v[210:213], v[20:23]
	v_mfma_f32_16x16x32_bf16 v[16:19], v[180:183], v[210:213], v[16:19]
	v_mfma_f32_16x16x32_bf16 v[4:7], v[172:175], v[228:231], v[4:7]
	v_mfma_f32_16x16x32_bf16 v[0:3], v[180:183], v[228:231], v[0:3]
	s_setprio 0
	s_barrier
	s_add_i32 s42, s42, 2
	s_add_u32 s10, s10, 0x100
	s_addc_u32 s11, s11, 0
	s_add_u32 s25, s25, 0x100
	s_addc_u32 s41, s41, 0
	s_cmp_gt_u32 s42, 61
	s_cbranch_scc0 .LBB0_260
	s_and_b64 vcc, exec, s[20:21]
	s_cbranch_vccz .LBB0_263
	s_barrier

; #define PG8_STAGE(bufoff, gbase, voff) do { _Pragma("unroll") for (int _i = 0; _i < 2; ++_i) \
;         __builtin_amdgcn_global_load_lds((const unsigned*)((const char*)(gbase) + (voff)[_i]), (LAS unsigned*)(lds + (bufoff) + ldsw + _i * 8192), 16, 0, 0); } while (0)
; #define PG8_LDA(dst, b, h) do { _Pragma("unroll") for (int m = 0; m < 4; ++m) _Pragma("unroll") for (int k = 0; k < 2; ++k) dst[m][k] = *(const LAS bf16x8*)(lds + PG8_SA(b, h) + aoff + m * 2048 + k * 1024); } while (0)
; #define PG8_LDB(dst, b, h) do { _Pragma("unroll") for (int n = 0; n < 2; ++n) _Pragma("unroll") for (int k = 0; k < 2; ++k) dst[n][k] = *(const LAS bf16x8*)(lds + PG8_SB(b, h) + boff + n * 2048 + k * 1024); } while (0)
; #define PG8_MMA(ai, bj, At, Bt) do { __builtin_amdgcn_s_setprio(1); _Pragma("unroll") for (int m = 0; m < 4; ++m) _Pragma("unroll") for (int n = 0; n < 2; ++n) _Pragma("unroll") for (int k = 0; k < 2; ++k) \
;         acc[ai][bj][m][n] = __builtin_amdgcn_mfma_f32_16x16x32_bf16(Bt[n][k], At[m][k], acc[ai][bj][m][n], 0, 0, 0); __builtin_amdgcn_s_setprio(0); } while (0)
; #define PG8_WAIT_V(n) asm volatile("s_waitcnt vmcnt(" #n ")" ::: "memory")
; #define PG8_WAIT_L(n) asm volatile("s_waitcnt lgkmcnt(" #n ")" ::: "memory")
; #define PG8_BAR __builtin_amdgcn_s_barrier()
; #define PG8_SCHED __builtin_amdgcn_sched_barrier(0)
; template <class Epi, class Sched, bool ALIGN_EPI = false, bool SP2 = false>
; __device__ __forceinline__ void gemm_phase(LAS unsigned char* lds, const Gemm g, const Sched& S, const Epi& E) {
;     ...
;             PG8_LDB(B0, 0, 0); PG8_LDB(B1, 0, 1); PG8_SCHED; PG8_LDA(At, 0, 0); PG8_STAGE(PG8_SA(1, 1), a1 + hstep, voffA);
;             PG8_WAIT_V(8); PG8_WAIT_L(0); PG8_BAR; PG8_MMA(0, 0, At, B0); PG8_MMA(0, 1, At, B1); PG8_BAR; PG8_SCHED;
;             PG8_LDA(At, 0, 1); PG8_STAGE(PG8_SB(0, 0), b2, voffB); PG8_STAGE(PG8_SB(0, 1), b2 + hstep, voffB); PG8_STAGE(PG8_SA(0, 0), a2, voffA);
.LBB0_424:
	s_add_u32 s100, s10, 0xfff00000
	s_addc_u32 s101, s11, -1
	s_add_u32 s12, s10, 0xfff00080
	s_addc_u32 s13, s11, -1
	s_add_i32 s48, 0, 0x10000
	s_cmp_eq_u32 s42, 60
	s_cselect_b32 s15, s2, s13
	s_cselect_b32 s14, s3, s12
	v_add_u32_e32 v146, s48, v149
	s_cselect_b32 s13, s17, s41
	s_cselect_b32 s12, s23, s25
	s_add_i32 s90, 0, 0x14000
	ds_read_b128 v[142:145], v146
	ds_read_b128 v[156:159], v146 offset:1024
	ds_read_b128 v[160:163], v146 offset:2048
	ds_read_b128 v[164:167], v146 offset:3072
	v_add_u32_e32 v146, s90, v149
	ds_read_b128 v[168:171], v146
	ds_read_b128 v[172:175], v146 offset:1024
	ds_read_b128 v[176:179], v146 offset:2048
	ds_read_b128 v[180:183], v146 offset:3072
	s_add_i32 m0, s34, 0xc000
	ds_read_b128 v[184:187], v155
	ds_read_b128 v[188:191], v155 offset:1024
	ds_read_b128 v[198:201], v155 offset:2048
	ds_read_b128 v[202:205], v155 offset:3072
	ds_read_b128 v[206:209], v155 offset:4096
	ds_read_b128 v[210:213], v155 offset:5120
	ds_read_b128 v[214:217], v155 offset:6144
	ds_read_b128 v[228:231], v155 offset:7168
	s_mov_b32 m0, s39
	s_nop 0
	global_load_lds_dwordx4 v130, s[100:101]
	s_add_i32 m0, s34, 0xc000
	s_nop 0
	global_load_lds_dwordx4 v138, s[10:11]
	s_add_i32 m0, s34, 0xe000
	s_nop 0
	global_load_lds_dwordx4 v140, s[10:11]
	s_waitcnt vmcnt(8)
	s_waitcnt lgkmcnt(0)
	s_barrier
	s_setprio 1
	s_waitcnt lgkmcnt(0)
	v_mfma_f32_16x16x32_bf16 v[124:127], v[142:145], v[184:187], v[124:127]
	v_mfma_f32_16x16x32_bf16 v[120:123], v[160:163], v[184:187], v[120:123]
	v_mfma_f32_16x16x32_bf16 v[108:111], v[142:145], v[198:201], v[108:111]
	v_mfma_f32_16x16x32_bf16 v[104:107], v[160:163], v[198:201], v[104:107]
	v_mfma_f32_16x16x32_bf16 v[92:95], v[142:145], v[206:209], v[92:95]
	v_mfma_f32_16x16x32_bf16 v[88:91], v[160:163], v[206:209], v[88:91]
	v_mfma_f32_16x16x32_bf16 v[76:79], v[142:145], v[214:217], v[76:79]
	v_mfma_f32_16x16x32_bf16 v[72:75], v[160:163], v[214:217], v[72:75]
	v_mfma_f32_16x16x32_bf16 v[124:127], v[156:159], v[188:191], v[124:127]
	v_mfma_f32_16x16x32_bf16 v[120:123], v[164:167], v[188:191], v[120:123]
	v_mfma_f32_16x16x32_bf16 v[108:111], v[156:159], v[202:205], v[108:111]
	v_mfma_f32_16x16x32_bf16 v[104:107], v[164:167], v[202:205], v[104:107]
	v_mfma_f32_16x16x32_bf16 v[92:95], v[156:159], v[210:213], v[92:95]
	v_mfma_f32_16x16x32_bf16 v[88:91], v[164:167], v[210:213], v[88:91]
	v_mfma_f32_16x16x32_bf16 v[76:79], v[156:159], v[228:231], v[76:79]
	v_mfma_f32_16x16x32_bf16 v[72:75], v[164:167], v[228:231], v[72:75]
	s_setprio 0
	s_setprio 1
	v_mfma_f32_16x16x32_bf16 v[116:119], v[168:171], v[184:187], v[116:119]
	v_mfma_f32_16x16x32_bf16 v[112:115], v[176:179], v[184:187], v[112:115]
	v_mfma_f32_16x16x32_bf16 v[100:103], v[168:171], v[198:201], v[100:103]
	v_mfma_f32_16x16x32_bf16 v[96:99], v[176:179], v[198:201], v[96:99]
	v_mfma_f32_16x16x32_bf16 v[84:87], v[168:171], v[206:209], v[84:87]
	v_mfma_f32_16x16x32_bf16 v[80:83], v[176:179], v[206:209], v[80:83]
	v_mfma_f32_16x16x32_bf16 v[68:71], v[168:171], v[214:217], v[68:71]
	v_mfma_f32_16x16x32_bf16 v[64:67], v[176:179], v[214:217], v[64:67]
	v_mfma_f32_16x16x32_bf16 v[116:119], v[172:175], v[188:191], v[116:119]
	v_mfma_f32_16x16x32_bf16 v[112:115], v[180:183], v[188:191], v[112:115]
	v_mfma_f32_16x16x32_bf16 v[100:103], v[172:175], v[202:205], v[100:103]
	v_mfma_f32_16x16x32_bf16 v[96:99], v[180:183], v[202:205], v[96:99]
	v_mfma_f32_16x16x32_bf16 v[84:87], v[172:175], v[210:213], v[84:87]
	v_mfma_f32_16x16x32_bf16 v[80:83], v[180:183], v[210:213], v[80:83]
	v_mfma_f32_16x16x32_bf16 v[68:71], v[172:175], v[228:231], v[68:71]
	v_mfma_f32_16x16x32_bf16 v[64:67], v[180:183], v[228:231], v[64:67]
	s_setprio 0
	s_barrier
	s_add_u32 s98, s12, 0x80
	s_addc_u32 s99, s13, 0
	s_add_u32 s100, s14, 0x80
	s_addc_u32 s101, s15, 0
	s_add_i32 s44, s48, s7
	s_mov_b32 m0, s44
	ds_read_b128 v[184:187], v155 offset:16384
	ds_read_b128 v[188:191], v155 offset:17408
	ds_read_b128 v[198:201], v155 offset:18432
	ds_read_b128 v[202:205], v155 offset:19456
	ds_read_b128 v[206:209], v155 offset:20480
	ds_read_b128 v[210:213], v155 offset:21504
	ds_read_b128 v[214:217], v155 offset:22528
	ds_read_b128 v[228:231], v155 offset:23552
	global_load_lds_dwordx4 v196, s[12:13]
	s_add_i32 m0, s44, 0x2000
	s_add_u32 s46, s12, 0x100000
	s_addc_u32 s47, s13, 0
	s_add_i32 s44, s90, s7
	global_load_lds_dwordx4 v132, s[12:13]
	s_mov_b32 m0, s44
	s_nop 0
	global_load_lds_dwordx4 v196, s[46:47]
	s_add_i32 m0, s44, 0x2000
	s_nop 0
	global_load_lds_dwordx4 v132, s[46:47]
	s_mov_b32 m0, s34
	s_nop 0
	global_load_lds_dwordx4 v128, s[14:15]
	s_waitcnt vmcnt(7)
	s_waitcnt lgkmcnt(0)
	s_barrier
; #define PG8_STAGE(bufoff, gbase, voff) do { _Pragma("unroll") for (int _i = 0; _i < 2; ++_i) \
;         __builtin_amdgcn_global_load_lds((const unsigned*)((const char*)(gbase) + (voff)[_i]), (LAS unsigned*)(lds + (bufoff) + ldsw + _i * 8192), 16, 0, 0); } while (0)
; #define PG8_LDA(dst, b, h) do { _Pragma("unroll") for (int m = 0; m < 4; ++m) _Pragma("unroll") for (int k = 0; k < 2; ++k) dst[m][k] = *(const LAS bf16x8*)(lds + PG8_SA(b, h) + aoff + m * 2048 + k * 1024); } while (0)
; #define PG8_LDB(dst, b, h) do { _Pragma("unroll") for (int n = 0; n < 2; ++n) _Pragma("unroll") for (int k = 0; k < 2; ++k) dst[n][k] = *(const LAS bf16x8*)(lds + PG8_SB(b, h) + boff + n * 2048 + k * 1024); } while (0)
; #define PG8_MMA(ai, bj, At, Bt) do { __builtin_amdgcn_s_setprio(1); _Pragma("unroll") for (int m = 0; m < 4; ++m) _Pragma("unroll") for (int n = 0; n < 2; ++n) _Pragma("unroll") for (int k = 0; k < 2; ++k) \
;         acc[ai][bj][m][n] = __builtin_amdgcn_mfma_f32_16x16x32_bf16(Bt[n][k], At[m][k], acc[ai][bj][m][n], 0, 0, 0); __builtin_amdgcn_s_setprio(0); } while (0)
; #define PG8_WAIT_V(n) asm volatile("s_waitcnt vmcnt(" #n ")" ::: "memory")
; #define PG8_WAIT_L(n) asm volatile("s_waitcnt lgkmcnt(" #n ")" ::: "memory")
; #define PG8_BAR __builtin_amdgcn_s_barrier()
; #define PG8_SCHED __builtin_amdgcn_sched_barrier(0)
; template <class Epi, class Sched, bool ALIGN_EPI = false, bool SP2 = false>
; __device__ __forceinline__ void gemm_phase(LAS unsigned char* lds, const Gemm g, const Sched& S, const Epi& E) {
;     ...
;             PG8_WAIT_V(8); PG8_WAIT_L(0); PG8_BAR; PG8_MMA(1, 0, At, B0); PG8_MMA(1, 1, At, B1); PG8_BAR; PG8_SCHED;
;             PG8_LDB(B0, 1, 0); PG8_LDB(B1, 1, 1); PG8_SCHED; PG8_LDA(At, 1, 0); PG8_STAGE(PG8_SA(0, 1), a2 + hstep, voffA);
	s_setprio 1
	s_waitcnt lgkmcnt(0)
	v_mfma_f32_16x16x32_bf16 v[60:63], v[142:145], v[184:187], v[60:63]
	v_mfma_f32_16x16x32_bf16 v[56:59], v[160:163], v[184:187], v[56:59]
	v_mfma_f32_16x16x32_bf16 v[44:47], v[142:145], v[198:201], v[44:47]
	v_mfma_f32_16x16x32_bf16 v[40:43], v[160:163], v[198:201], v[40:43]
	v_mfma_f32_16x16x32_bf16 v[28:31], v[142:145], v[206:209], v[28:31]
	v_mfma_f32_16x16x32_bf16 v[24:27], v[160:163], v[206:209], v[24:27]
	v_mfma_f32_16x16x32_bf16 v[12:15], v[142:145], v[214:217], v[12:15]
	v_mfma_f32_16x16x32_bf16 v[8:11], v[160:163], v[214:217], v[8:11]
	v_mfma_f32_16x16x32_bf16 v[60:63], v[156:159], v[188:191], v[60:63]
	v_mfma_f32_16x16x32_bf16 v[56:59], v[164:167], v[188:191], v[56:59]
	v_mfma_f32_16x16x32_bf16 v[44:47], v[156:159], v[202:205], v[44:47]
	v_mfma_f32_16x16x32_bf16 v[40:43], v[164:167], v[202:205], v[40:43]
	v_mfma_f32_16x16x32_bf16 v[28:31], v[156:159], v[210:213], v[28:31]
	v_mfma_f32_16x16x32_bf16 v[24:27], v[164:167], v[210:213], v[24:27]
	v_mfma_f32_16x16x32_bf16 v[12:15], v[156:159], v[228:231], v[12:15]
	v_mfma_f32_16x16x32_bf16 v[8:11], v[164:167], v[228:231], v[8:11]
	s_setprio 0
	s_setprio 1
	v_mfma_f32_16x16x32_bf16 v[52:55], v[168:171], v[184:187], v[52:55]
	v_mfma_f32_16x16x32_bf16 v[48:51], v[176:179], v[184:187], v[48:51]
	v_mfma_f32_16x16x32_bf16 v[36:39], v[168:171], v[198:201], v[36:39]
	v_mfma_f32_16x16x32_bf16 v[32:35], v[176:179], v[198:201], v[32:35]
	v_mfma_f32_16x16x32_bf16 v[20:23], v[168:171], v[206:209], v[20:23]
	v_mfma_f32_16x16x32_bf16 v[16:19], v[176:179], v[206:209], v[16:19]
	v_mfma_f32_16x16x32_bf16 v[4:7], v[168:171], v[214:217], v[4:7]
	v_mfma_f32_16x16x32_bf16 v[0:3], v[176:179], v[214:217], v[0:3]
	v_mfma_f32_16x16x32_bf16 v[52:55], v[172:175], v[188:191], v[52:55]
	v_mfma_f32_16x16x32_bf16 v[48:51], v[180:183], v[188:191], v[48:51]
	v_mfma_f32_16x16x32_bf16 v[36:39], v[172:175], v[202:205], v[36:39]
	v_mfma_f32_16x16x32_bf16 v[32:35], v[180:183], v[202:205], v[32:35]
	v_mfma_f32_16x16x32_bf16 v[20:23], v[172:175], v[210:213], v[20:23]
	v_mfma_f32_16x16x32_bf16 v[16:19], v[180:183], v[210:213], v[16:19]
	v_mfma_f32_16x16x32_bf16 v[4:7], v[172:175], v[228:231], v[4:7]
	v_mfma_f32_16x16x32_bf16 v[0:3], v[180:183], v[228:231], v[0:3]
	s_setprio 0
	s_barrier
	s_add_i32 s91, 0, 0x18000
	s_add_i32 s58, 0, 0x1c000
	v_add_u32_e32 v164, s91, v149
	v_add_u32_e32 v180, s58, v149
	ds_read_b128 v[142:145], v164
	ds_read_b128 v[156:159], v164 offset:1024
	ds_read_b128 v[160:163], v164 offset:2048
	ds_read_b128 v[164:167], v164 offset:3072
	ds_read_b128 v[168:171], v180
	ds_read_b128 v[172:175], v180 offset:1024
	ds_read_b128 v[176:179], v180 offset:2048
	ds_read_b128 v[180:183], v180 offset:3072
	s_mov_b32 m0, s35
	s_nop 0
	global_load_lds_dwordx4 v130, s[14:15]
	s_add_u32 s14, s14, 0x100000
	s_addc_u32 s15, s15, 0
	s_mov_b32 m0, s36
	ds_read_b128 v[184:187], v155 offset:32768
	ds_read_b128 v[188:191], v155 offset:33792
	ds_read_b128 v[198:201], v155 offset:34816
	ds_read_b128 v[202:205], v155 offset:35840
	ds_read_b128 v[206:209], v155 offset:36864
	ds_read_b128 v[210:213], v155 offset:37888
	ds_read_b128 v[214:217], v155 offset:38912
	ds_read_b128 v[228:231], v155 offset:39936
	global_load_lds_dwordx4 v128, s[14:15]
	s_mov_b32 m0, s37
	s_nop 0
	global_load_lds_dwordx4 v130, s[14:15]
	s_waitcnt vmcnt(8)
	s_waitcnt lgkmcnt(0)
	s_barrier
; #define PG8_STAGE(bufoff, gbase, voff) do { _Pragma("unroll") for (int _i = 0; _i < 2; ++_i) \
;         __builtin_amdgcn_global_load_lds((const unsigned*)((const char*)(gbase) + (voff)[_i]), (LAS unsigned*)(lds + (bufoff) + ldsw + _i * 8192), 16, 0, 0); } while (0)
; #define PG8_LDA(dst, b, h) do { _Pragma("unroll") for (int m = 0; m < 4; ++m) _Pragma("unroll") for (int k = 0; k < 2; ++k) dst[m][k] = *(const LAS bf16x8*)(lds + PG8_SA(b, h) + aoff + m * 2048 + k * 1024); } while (0)
; #define PG8_MMA(ai, bj, At, Bt) do { __builtin_amdgcn_s_setprio(1); _Pragma("unroll") for (int m = 0; m < 4; ++m) _Pragma("unroll") for (int n = 0; n < 2; ++n) _Pragma("unroll") for (int k = 0; k < 2; ++k) \
;         acc[ai][bj][m][n] = __builtin_amdgcn_mfma_f32_16x16x32_bf16(Bt[n][k], At[m][k], acc[ai][bj][m][n], 0, 0, 0); __builtin_amdgcn_s_setprio(0); } while (0)
; #define PG8_WAIT_V(n) asm volatile("s_waitcnt vmcnt(" #n ")" ::: "memory")
; #define PG8_WAIT_L(n) asm volatile("s_waitcnt lgkmcnt(" #n ")" ::: "memory")
; #define PG8_BAR __builtin_amdgcn_s_barrier()
; #define PG8_SCHED __builtin_amdgcn_sched_barrier(0)
; template <class Epi, class Sched, bool ALIGN_EPI = false, bool SP2 = false>
; __device__ __forceinline__ void gemm_phase(LAS unsigned char* lds, const Gemm g, const Sched& S, const Epi& E) {
;     ...
;             PG8_WAIT_V(8); PG8_WAIT_L(0); PG8_BAR; PG8_MMA(0, 0, At, B0); PG8_MMA(0, 1, At, B1); PG8_BAR; PG8_SCHED;
;             PG8_LDA(At, 1, 1); PG8_STAGE(PG8_SB(1, 0), b3, voffB); PG8_STAGE(PG8_SB(1, 1), b3 + hstep, voffB); PG8_STAGE(PG8_SA(1, 0), a3, voffA);
;             PG8_WAIT_V(8); PG8_WAIT_L(0); PG8_BAR; PG8_MMA(1, 0, At, B0); PG8_MMA(1, 1, At, B1); PG8_BAR; PG8_SCHED;
	s_setprio 1
	s_waitcnt lgkmcnt(0)
	v_mfma_f32_16x16x32_bf16 v[124:127], v[142:145], v[184:187], v[124:127]
	v_mfma_f32_16x16x32_bf16 v[120:123], v[160:163], v[184:187], v[120:123]
	v_mfma_f32_16x16x32_bf16 v[108:111], v[142:145], v[198:201], v[108:111]
	v_mfma_f32_16x16x32_bf16 v[104:107], v[160:163], v[198:201], v[104:107]
	v_mfma_f32_16x16x32_bf16 v[92:95], v[142:145], v[206:209], v[92:95]
	v_mfma_f32_16x16x32_bf16 v[88:91], v[160:163], v[206:209], v[88:91]
	v_mfma_f32_16x16x32_bf16 v[76:79], v[142:145], v[214:217], v[76:79]
	v_mfma_f32_16x16x32_bf16 v[72:75], v[160:163], v[214:217], v[72:75]
	v_mfma_f32_16x16x32_bf16 v[124:127], v[156:159], v[188:191], v[124:127]
	v_mfma_f32_16x16x32_bf16 v[120:123], v[164:167], v[188:191], v[120:123]
	v_mfma_f32_16x16x32_bf16 v[108:111], v[156:159], v[202:205], v[108:111]
	v_mfma_f32_16x16x32_bf16 v[104:107], v[164:167], v[202:205], v[104:107]
	v_mfma_f32_16x16x32_bf16 v[92:95], v[156:159], v[210:213], v[92:95]
	v_mfma_f32_16x16x32_bf16 v[88:91], v[164:167], v[210:213], v[88:91]
	v_mfma_f32_16x16x32_bf16 v[76:79], v[156:159], v[228:231], v[76:79]
	v_mfma_f32_16x16x32_bf16 v[72:75], v[164:167], v[228:231], v[72:75]
	s_setprio 0
	s_setprio 1
	v_mfma_f32_16x16x32_bf16 v[116:119], v[168:171], v[184:187], v[116:119]
	v_mfma_f32_16x16x32_bf16 v[112:115], v[176:179], v[184:187], v[112:115]
	v_mfma_f32_16x16x32_bf16 v[100:103], v[168:171], v[198:201], v[100:103]
	v_mfma_f32_16x16x32_bf16 v[96:99], v[176:179], v[198:201], v[96:99]
	v_mfma_f32_16x16x32_bf16 v[84:87], v[168:171], v[206:209], v[84:87]
	v_mfma_f32_16x16x32_bf16 v[80:83], v[176:179], v[206:209], v[80:83]
	v_mfma_f32_16x16x32_bf16 v[68:71], v[168:171], v[214:217], v[68:71]
	v_mfma_f32_16x16x32_bf16 v[64:67], v[176:179], v[214:217], v[64:67]
	v_mfma_f32_16x16x32_bf16 v[116:119], v[172:175], v[188:191], v[116:119]
	v_mfma_f32_16x16x32_bf16 v[112:115], v[180:183], v[188:191], v[112:115]
	v_mfma_f32_16x16x32_bf16 v[100:103], v[172:175], v[202:205], v[100:103]
	v_mfma_f32_16x16x32_bf16 v[96:99], v[180:183], v[202:205], v[96:99]
	v_mfma_f32_16x16x32_bf16 v[84:87], v[172:175], v[210:213], v[84:87]
	v_mfma_f32_16x16x32_bf16 v[80:83], v[180:183], v[210:213], v[80:83]
	v_mfma_f32_16x16x32_bf16 v[68:71], v[172:175], v[228:231], v[68:71]
	v_mfma_f32_16x16x32_bf16 v[64:67], v[180:183], v[228:231], v[64:67]
	s_setprio 0
	s_barrier
	s_add_i32 s14, s91, s7
	s_mov_b32 m0, s14
	ds_read_b128 v[184:187], v155 offset:49152
	ds_read_b128 v[188:191], v155 offset:50176
	ds_read_b128 v[198:201], v155 offset:51200
	ds_read_b128 v[202:205], v155 offset:52224
	ds_read_b128 v[206:209], v155 offset:53248
	ds_read_b128 v[210:213], v155 offset:54272
	ds_read_b128 v[214:217], v155 offset:55296
	ds_read_b128 v[228:231], v155 offset:56320
	global_load_lds_dwordx4 v196, s[98:99]
	s_add_i32 m0, s14, 0x2000
	s_add_u32 s12, s12, 0x100080
	s_addc_u32 s13, s13, 0
	s_add_i32 s14, s58, s7
	global_load_lds_dwordx4 v132, s[98:99]
	s_mov_b32 m0, s14
	s_nop 0
	global_load_lds_dwordx4 v196, s[12:13]
	s_add_i32 m0, s14, 0x2000
	s_nop 0
	global_load_lds_dwordx4 v132, s[12:13]
	s_mov_b32 m0, s38
	s_nop 0
	global_load_lds_dwordx4 v128, s[100:101]
	s_waitcnt vmcnt(7)
	s_waitcnt lgkmcnt(0)
	s_barrier
	s_setprio 1
	s_waitcnt lgkmcnt(0)
	v_mfma_f32_16x16x32_bf16 v[60:63], v[142:145], v[184:187], v[60:63]
	v_mfma_f32_16x16x32_bf16 v[56:59], v[160:163], v[184:187], v[56:59]
	v_mfma_f32_16x16x32_bf16 v[44:47], v[142:145], v[198:201], v[44:47]
	v_mfma_f32_16x16x32_bf16 v[40:43], v[160:163], v[198:201], v[40:43]
	v_mfma_f32_16x16x32_bf16 v[28:31], v[142:145], v[206:209], v[28:31]
	v_mfma_f32_16x16x32_bf16 v[24:27], v[160:163], v[206:209], v[24:27]
	v_mfma_f32_16x16x32_bf16 v[12:15], v[142:145], v[214:217], v[12:15]
	v_mfma_f32_16x16x32_bf16 v[8:11], v[160:163], v[214:217], v[8:11]
	v_mfma_f32_16x16x32_bf16 v[60:63], v[156:159], v[188:191], v[60:63]
	v_mfma_f32_16x16x32_bf16 v[56:59], v[164:167], v[188:191], v[56:59]
	v_mfma_f32_16x16x32_bf16 v[44:47], v[156:159], v[202:205], v[44:47]
	v_mfma_f32_16x16x32_bf16 v[40:43], v[164:167], v[202:205], v[40:43]
	v_mfma_f32_16x16x32_bf16 v[28:31], v[156:159], v[210:213], v[28:31]
	v_mfma_f32_16x16x32_bf16 v[24:27], v[164:167], v[210:213], v[24:27]
	v_mfma_f32_16x16x32_bf16 v[12:15], v[156:159], v[228:231], v[12:15]
	v_mfma_f32_16x16x32_bf16 v[8:11], v[164:167], v[228:231], v[8:11]
	s_setprio 0
	s_setprio 1
	v_mfma_f32_16x16x32_bf16 v[52:55], v[168:171], v[184:187], v[52:55]
	v_mfma_f32_16x16x32_bf16 v[48:51], v[176:179], v[184:187], v[48:51]
	v_mfma_f32_16x16x32_bf16 v[36:39], v[168:171], v[198:201], v[36:39]
	v_mfma_f32_16x16x32_bf16 v[32:35], v[176:179], v[198:201], v[32:35]
	v_mfma_f32_16x16x32_bf16 v[20:23], v[168:171], v[206:209], v[20:23]
	v_mfma_f32_16x16x32_bf16 v[16:19], v[176:179], v[206:209], v[16:19]
	v_mfma_f32_16x16x32_bf16 v[4:7], v[168:171], v[214:217], v[4:7]
	v_mfma_f32_16x16x32_bf16 v[0:3], v[176:179], v[214:217], v[0:3]
	v_mfma_f32_16x16x32_bf16 v[52:55], v[172:175], v[188:191], v[52:55]
	v_mfma_f32_16x16x32_bf16 v[48:51], v[180:183], v[188:191], v[48:51]
	v_mfma_f32_16x16x32_bf16 v[36:39], v[172:175], v[202:205], v[36:39]
	v_mfma_f32_16x16x32_bf16 v[32:35], v[180:183], v[202:205], v[32:35]
	v_mfma_f32_16x16x32_bf16 v[20:23], v[172:175], v[210:213], v[20:23]
	v_mfma_f32_16x16x32_bf16 v[16:19], v[180:183], v[210:213], v[16:19]
	v_mfma_f32_16x16x32_bf16 v[4:7], v[172:175], v[228:231], v[4:7]
	v_mfma_f32_16x16x32_bf16 v[0:3], v[180:183], v[228:231], v[0:3]
	s_setprio 0
	s_barrier
	s_add_i32 s42, s42, 2
	s_add_u32 s10, s10, 0x100
	s_addc_u32 s11, s11, 0
	s_add_u32 s25, s25, 0x100
	s_addc_u32 s41, s41, 0
	s_cmp_gt_u32 s42, 61
	s_cbranch_scc0 .LBB0_424
	s_and_b64 vcc, exec, s[20:21]
	s_cbranch_vccz .LBB0_427
	s_barrier

; #define PG8_STAGE(bufoff, gbase, voff) do { _Pragma("unroll") for (int _i = 0; _i < 2; ++_i) \
;         __builtin_amdgcn_global_load_lds((const unsigned*)((const char*)(gbase) + (voff)[_i]), (LAS unsigned*)(lds + (bufoff) + ldsw + _i * 8192), 16, 0, 0); } while (0)
; #define PG8_LDA(dst, b, h) do { _Pragma("unroll") for (int m = 0; m < 4; ++m) _Pragma("unroll") for (int k = 0; k < 2; ++k) dst[m][k] = *(const LAS bf16x8*)(lds + PG8_SA(b, h) + aoff + m * 2048 + k * 1024); } while (0)
; #define PG8_LDB(dst, b, h) do { _Pragma("unroll") for (int n = 0; n < 2; ++n) _Pragma("unroll") for (int k = 0; k < 2; ++k) dst[n][k] = *(const LAS bf16x8*)(lds + PG8_SB(b, h) + boff + n * 2048 + k * 1024); } while (0)
; #define PG8_MMA(ai, bj, At, Bt) do { __builtin_amdgcn_s_setprio(1); _Pragma("unroll") for (int m = 0; m < 4; ++m) _Pragma("unroll") for (int n = 0; n < 2; ++n) _Pragma("unroll") for (int k = 0; k < 2; ++k) \
;         acc[ai][bj][m][n] = __builtin_amdgcn_mfma_f32_16x16x32_bf16(Bt[n][k], At[m][k], acc[ai][bj][m][n], 0, 0, 0); __builtin_amdgcn_s_setprio(0); } while (0)
; #define PG8_WAIT_V(n) asm volatile("s_waitcnt vmcnt(" #n ")" ::: "memory")
; #define PG8_WAIT_L(n) asm volatile("s_waitcnt lgkmcnt(" #n ")" ::: "memory")
; #define PG8_BAR __builtin_amdgcn_s_barrier()
; #define PG8_SCHED __builtin_amdgcn_sched_barrier(0)
; template <class Epi, class Sched, bool ALIGN_EPI = false, bool SP2 = false>
; __device__ __forceinline__ void gemm_phase(LAS unsigned char* lds, const Gemm g, const Sched& S, const Epi& E) {
;     ...
;             PG8_LDB(B0, 0, 0); PG8_LDB(B1, 0, 1); PG8_SCHED; PG8_LDA(At, 0, 0); PG8_STAGE(PG8_SA(1, 1), a1 + hstep, voffA);
;             PG8_WAIT_V(8); PG8_WAIT_L(0); PG8_BAR; PG8_MMA(0, 0, At, B0); PG8_MMA(0, 1, At, B1); PG8_BAR; PG8_SCHED;
;             PG8_LDA(At, 0, 1); PG8_STAGE(PG8_SB(0, 0), b2, voffB); PG8_STAGE(PG8_SB(0, 1), b2 + hstep, voffB); PG8_STAGE(PG8_SA(0, 0), a2, voffA);
.LBB0_510:
	v_add_u32_e32 v138, s48, v141
	ds_read_b128 v[144:147], v138
	ds_read_b128 v[148:151], v138 offset:1024
	ds_read_b128 v[152:155], v138 offset:2048
	ds_read_b128 v[156:159], v138 offset:3072
	v_add_u32_e32 v138, s90, v141
	ds_read_b128 v[160:163], v138
	ds_read_b128 v[164:167], v138 offset:1024
	ds_read_b128 v[168:171], v138 offset:2048
	ds_read_b128 v[172:175], v138 offset:3072
	s_add_u32 s100, s24, 0xfff00000
	s_addc_u32 s101, s25, -1
	s_add_u32 s26, s24, 0xfff00080
	s_addc_u32 s27, s25, -1
	s_cmp_eq_u32 s41, 60
	s_cselect_b32 s29, s19, s27
	s_cselect_b32 s28, s37, s26
	s_cselect_b32 s27, s15, s40
	s_cselect_b32 s26, s38, s39
	s_add_i32 m0, s3, 0xc000
	ds_read_b128 v[176:179], v143
	ds_read_b128 v[180:183], v143 offset:1024
	ds_read_b128 v[184:187], v143 offset:2048
	ds_read_b128 v[188:191], v143 offset:3072
	ds_read_b128 v[198:201], v143 offset:4096
	ds_read_b128 v[202:205], v143 offset:5120
	ds_read_b128 v[206:209], v143 offset:6144
	ds_read_b128 v[210:213], v143 offset:7168
	s_mov_b32 m0, s31
	s_nop 0
	global_load_lds_dwordx4 v130, s[100:101]
	s_add_i32 m0, s3, 0xc000
	s_nop 0
	global_load_lds_dwordx4 v134, s[24:25]
	s_add_i32 m0, s3, 0xe000
	s_nop 0
	global_load_lds_dwordx4 v136, s[24:25]
	s_waitcnt vmcnt(8)
	s_waitcnt lgkmcnt(0)
	s_barrier
	s_setprio 1
	s_waitcnt lgkmcnt(0)
	v_mfma_f32_16x16x32_bf16 v[124:127], v[144:147], v[176:179], v[124:127]
	v_mfma_f32_16x16x32_bf16 v[120:123], v[152:155], v[176:179], v[120:123]
	v_mfma_f32_16x16x32_bf16 v[116:119], v[144:147], v[184:187], v[116:119]
	v_mfma_f32_16x16x32_bf16 v[108:111], v[152:155], v[184:187], v[108:111]
	v_mfma_f32_16x16x32_bf16 v[100:103], v[144:147], v[198:201], v[100:103]
	v_mfma_f32_16x16x32_bf16 v[92:95], v[152:155], v[198:201], v[92:95]
	v_mfma_f32_16x16x32_bf16 v[80:83], v[144:147], v[206:209], v[80:83]
	v_mfma_f32_16x16x32_bf16 v[72:75], v[152:155], v[206:209], v[72:75]
	v_mfma_f32_16x16x32_bf16 v[124:127], v[148:151], v[180:183], v[124:127]
	v_mfma_f32_16x16x32_bf16 v[120:123], v[156:159], v[180:183], v[120:123]
	v_mfma_f32_16x16x32_bf16 v[116:119], v[148:151], v[188:191], v[116:119]
	v_mfma_f32_16x16x32_bf16 v[108:111], v[156:159], v[188:191], v[108:111]
	v_mfma_f32_16x16x32_bf16 v[100:103], v[148:151], v[202:205], v[100:103]
	v_mfma_f32_16x16x32_bf16 v[92:95], v[156:159], v[202:205], v[92:95]
	v_mfma_f32_16x16x32_bf16 v[80:83], v[148:151], v[210:213], v[80:83]
	v_mfma_f32_16x16x32_bf16 v[72:75], v[156:159], v[210:213], v[72:75]
	s_setprio 0
	s_setprio 1
	v_mfma_f32_16x16x32_bf16 v[112:115], v[160:163], v[176:179], v[112:115]
	v_mfma_f32_16x16x32_bf16 v[104:107], v[168:171], v[176:179], v[104:107]
	v_mfma_f32_16x16x32_bf16 v[96:99], v[160:163], v[184:187], v[96:99]
	v_mfma_f32_16x16x32_bf16 v[88:91], v[168:171], v[184:187], v[88:91]
	v_mfma_f32_16x16x32_bf16 v[84:87], v[160:163], v[198:201], v[84:87]
	v_mfma_f32_16x16x32_bf16 v[76:79], v[168:171], v[198:201], v[76:79]
	v_mfma_f32_16x16x32_bf16 v[68:71], v[160:163], v[206:209], v[68:71]
	v_mfma_f32_16x16x32_bf16 v[64:67], v[168:171], v[206:209], v[64:67]
	v_mfma_f32_16x16x32_bf16 v[112:115], v[164:167], v[180:183], v[112:115]
	v_mfma_f32_16x16x32_bf16 v[104:107], v[172:175], v[180:183], v[104:107]
	v_mfma_f32_16x16x32_bf16 v[96:99], v[164:167], v[188:191], v[96:99]
	v_mfma_f32_16x16x32_bf16 v[88:91], v[172:175], v[188:191], v[88:91]
	v_mfma_f32_16x16x32_bf16 v[84:87], v[164:167], v[202:205], v[84:87]
	v_mfma_f32_16x16x32_bf16 v[76:79], v[172:175], v[202:205], v[76:79]
	v_mfma_f32_16x16x32_bf16 v[68:71], v[164:167], v[210:213], v[68:71]
	v_mfma_f32_16x16x32_bf16 v[64:67], v[172:175], v[210:213], v[64:67]
	s_setprio 0
	s_barrier
	s_add_u32 s98, s26, 0x80
	s_addc_u32 s99, s27, 0
	s_add_u32 s100, s28, 0x80
	s_addc_u32 s101, s29, 0
	s_add_i32 s42, s48, s2
	s_mov_b32 m0, s42
	ds_read_b128 v[176:179], v143 offset:16384
	ds_read_b128 v[180:183], v143 offset:17408
	ds_read_b128 v[184:187], v143 offset:18432
	ds_read_b128 v[188:191], v143 offset:19456
	ds_read_b128 v[198:201], v143 offset:20480
	ds_read_b128 v[202:205], v143 offset:21504
	ds_read_b128 v[206:209], v143 offset:22528
	ds_read_b128 v[210:213], v143 offset:23552
	global_load_lds_dwordx4 v196, s[26:27]
	s_add_i32 m0, s42, 0x2000
	s_add_u32 s46, s26, 0x100000
	s_addc_u32 s47, s27, 0
	s_add_i32 s42, s90, s2
	global_load_lds_dwordx4 v128, s[26:27]
	s_mov_b32 m0, s42
	s_nop 0
	global_load_lds_dwordx4 v196, s[46:47]
	s_add_i32 m0, s42, 0x2000
	s_nop 0
	global_load_lds_dwordx4 v128, s[46:47]
	s_mov_b32 m0, s3
	s_nop 0
	global_load_lds_dwordx4 v132, s[28:29]
	s_waitcnt vmcnt(7)
	s_waitcnt lgkmcnt(0)
	s_barrier
; #define PG8_STAGE(bufoff, gbase, voff) do { _Pragma("unroll") for (int _i = 0; _i < 2; ++_i) \
;         __builtin_amdgcn_global_load_lds((const unsigned*)((const char*)(gbase) + (voff)[_i]), (LAS unsigned*)(lds + (bufoff) + ldsw + _i * 8192), 16, 0, 0); } while (0)
; #define PG8_LDA(dst, b, h) do { _Pragma("unroll") for (int m = 0; m < 4; ++m) _Pragma("unroll") for (int k = 0; k < 2; ++k) dst[m][k] = *(const LAS bf16x8*)(lds + PG8_SA(b, h) + aoff + m * 2048 + k * 1024); } while (0)
; #define PG8_LDB(dst, b, h) do { _Pragma("unroll") for (int n = 0; n < 2; ++n) _Pragma("unroll") for (int k = 0; k < 2; ++k) dst[n][k] = *(const LAS bf16x8*)(lds + PG8_SB(b, h) + boff + n * 2048 + k * 1024); } while (0)
; #define PG8_MMA(ai, bj, At, Bt) do { __builtin_amdgcn_s_setprio(1); _Pragma("unroll") for (int m = 0; m < 4; ++m) _Pragma("unroll") for (int n = 0; n < 2; ++n) _Pragma("unroll") for (int k = 0; k < 2; ++k) \
;         acc[ai][bj][m][n] = __builtin_amdgcn_mfma_f32_16x16x32_bf16(Bt[n][k], At[m][k], acc[ai][bj][m][n], 0, 0, 0); __builtin_amdgcn_s_setprio(0); } while (0)
; #define PG8_WAIT_V(n) asm volatile("s_waitcnt vmcnt(" #n ")" ::: "memory")
; #define PG8_WAIT_L(n) asm volatile("s_waitcnt lgkmcnt(" #n ")" ::: "memory")
; #define PG8_BAR __builtin_amdgcn_s_barrier()
; #define PG8_SCHED __builtin_amdgcn_sched_barrier(0)
; template <class Epi, class Sched, bool ALIGN_EPI = false, bool SP2 = false>
; __device__ __forceinline__ void gemm_phase(LAS unsigned char* lds, const Gemm g, const Sched& S, const Epi& E) {
;     ...
;             PG8_WAIT_V(8); PG8_WAIT_L(0); PG8_BAR; PG8_MMA(1, 0, At, B0); PG8_MMA(1, 1, At, B1); PG8_BAR; PG8_SCHED;
;             PG8_LDB(B0, 1, 0); PG8_LDB(B1, 1, 1); PG8_SCHED; PG8_LDA(At, 1, 0); PG8_STAGE(PG8_SA(0, 1), a2 + hstep, voffA);
;             PG8_WAIT_V(8); PG8_WAIT_L(0); PG8_BAR; PG8_MMA(0, 0, At, B0); PG8_MMA(0, 1, At, B1); PG8_BAR; PG8_SCHED;
	s_setprio 1
	s_waitcnt lgkmcnt(0)
	v_mfma_f32_16x16x32_bf16 v[60:63], v[144:147], v[176:179], v[60:63]
	v_mfma_f32_16x16x32_bf16 v[56:59], v[152:155], v[176:179], v[56:59]
	v_mfma_f32_16x16x32_bf16 v[52:55], v[144:147], v[184:187], v[52:55]
	v_mfma_f32_16x16x32_bf16 v[44:47], v[152:155], v[184:187], v[44:47]
	v_mfma_f32_16x16x32_bf16 v[36:39], v[144:147], v[198:201], v[36:39]
	v_mfma_f32_16x16x32_bf16 v[28:31], v[152:155], v[198:201], v[28:31]
	v_mfma_f32_16x16x32_bf16 v[20:23], v[144:147], v[206:209], v[20:23]
	v_mfma_f32_16x16x32_bf16 v[12:15], v[152:155], v[206:209], v[12:15]
	v_mfma_f32_16x16x32_bf16 v[60:63], v[148:151], v[180:183], v[60:63]
	v_mfma_f32_16x16x32_bf16 v[56:59], v[156:159], v[180:183], v[56:59]
	v_mfma_f32_16x16x32_bf16 v[52:55], v[148:151], v[188:191], v[52:55]
	v_mfma_f32_16x16x32_bf16 v[44:47], v[156:159], v[188:191], v[44:47]
	v_mfma_f32_16x16x32_bf16 v[36:39], v[148:151], v[202:205], v[36:39]
	v_mfma_f32_16x16x32_bf16 v[28:31], v[156:159], v[202:205], v[28:31]
	v_mfma_f32_16x16x32_bf16 v[20:23], v[148:151], v[210:213], v[20:23]
	v_mfma_f32_16x16x32_bf16 v[12:15], v[156:159], v[210:213], v[12:15]
	s_setprio 0
	s_setprio 1
	v_mfma_f32_16x16x32_bf16 v[48:51], v[160:163], v[176:179], v[48:51]
	v_mfma_f32_16x16x32_bf16 v[40:43], v[168:171], v[176:179], v[40:43]
	v_mfma_f32_16x16x32_bf16 v[32:35], v[160:163], v[184:187], v[32:35]
	v_mfma_f32_16x16x32_bf16 v[24:27], v[168:171], v[184:187], v[24:27]
	v_mfma_f32_16x16x32_bf16 v[16:19], v[160:163], v[198:201], v[16:19]
	v_mfma_f32_16x16x32_bf16 v[8:11], v[168:171], v[198:201], v[8:11]
	v_mfma_f32_16x16x32_bf16 v[4:7], v[160:163], v[206:209], v[4:7]
	v_mfma_f32_16x16x32_bf16 v[0:3], v[168:171], v[206:209], v[0:3]
	v_mfma_f32_16x16x32_bf16 v[48:51], v[164:167], v[180:183], v[48:51]
	v_mfma_f32_16x16x32_bf16 v[40:43], v[172:175], v[180:183], v[40:43]
	v_mfma_f32_16x16x32_bf16 v[32:35], v[164:167], v[188:191], v[32:35]
	v_mfma_f32_16x16x32_bf16 v[24:27], v[172:175], v[188:191], v[24:27]
	v_mfma_f32_16x16x32_bf16 v[16:19], v[164:167], v[202:205], v[16:19]
	v_mfma_f32_16x16x32_bf16 v[8:11], v[172:175], v[202:205], v[8:11]
	v_mfma_f32_16x16x32_bf16 v[4:7], v[164:167], v[210:213], v[4:7]
	v_mfma_f32_16x16x32_bf16 v[0:3], v[172:175], v[210:213], v[0:3]
	s_setprio 0
	s_barrier
	v_add_u32_e32 v156, s91, v141
	v_add_u32_e32 v172, s58, v141
	ds_read_b128 v[144:147], v156
	ds_read_b128 v[148:151], v156 offset:1024
	ds_read_b128 v[152:155], v156 offset:2048
	ds_read_b128 v[156:159], v156 offset:3072
	ds_read_b128 v[160:163], v172
	ds_read_b128 v[164:167], v172 offset:1024
	ds_read_b128 v[168:171], v172 offset:2048
	ds_read_b128 v[172:175], v172 offset:3072
	s_mov_b32 m0, s6
	s_nop 0
	global_load_lds_dwordx4 v130, s[28:29]
	s_add_u32 s28, s28, 0x100000
	s_addc_u32 s29, s29, 0
	s_mov_b32 m0, s7
	ds_read_b128 v[176:179], v143 offset:32768
	ds_read_b128 v[180:183], v143 offset:33792
	ds_read_b128 v[184:187], v143 offset:34816
	ds_read_b128 v[188:191], v143 offset:35840
	ds_read_b128 v[198:201], v143 offset:36864
	ds_read_b128 v[202:205], v143 offset:37888
	ds_read_b128 v[206:209], v143 offset:38912
	ds_read_b128 v[210:213], v143 offset:39936
	global_load_lds_dwordx4 v132, s[28:29]
	s_mov_b32 m0, s17
	s_nop 0
	global_load_lds_dwordx4 v130, s[28:29]
	s_waitcnt vmcnt(8)
	s_waitcnt lgkmcnt(0)
	s_barrier
	s_setprio 1
	s_waitcnt lgkmcnt(0)
	v_mfma_f32_16x16x32_bf16 v[124:127], v[144:147], v[176:179], v[124:127]
	v_mfma_f32_16x16x32_bf16 v[120:123], v[152:155], v[176:179], v[120:123]
	v_mfma_f32_16x16x32_bf16 v[116:119], v[144:147], v[184:187], v[116:119]
	v_mfma_f32_16x16x32_bf16 v[108:111], v[152:155], v[184:187], v[108:111]
	v_mfma_f32_16x16x32_bf16 v[100:103], v[144:147], v[198:201], v[100:103]
	v_mfma_f32_16x16x32_bf16 v[92:95], v[152:155], v[198:201], v[92:95]
	v_mfma_f32_16x16x32_bf16 v[80:83], v[144:147], v[206:209], v[80:83]
	v_mfma_f32_16x16x32_bf16 v[72:75], v[152:155], v[206:209], v[72:75]
	v_mfma_f32_16x16x32_bf16 v[124:127], v[148:151], v[180:183], v[124:127]
	v_mfma_f32_16x16x32_bf16 v[120:123], v[156:159], v[180:183], v[120:123]
	v_mfma_f32_16x16x32_bf16 v[116:119], v[148:151], v[188:191], v[116:119]
	v_mfma_f32_16x16x32_bf16 v[108:111], v[156:159], v[188:191], v[108:111]
	v_mfma_f32_16x16x32_bf16 v[100:103], v[148:151], v[202:205], v[100:103]
	v_mfma_f32_16x16x32_bf16 v[92:95], v[156:159], v[202:205], v[92:95]
	v_mfma_f32_16x16x32_bf16 v[80:83], v[148:151], v[210:213], v[80:83]
	v_mfma_f32_16x16x32_bf16 v[72:75], v[156:159], v[210:213], v[72:75]
	s_setprio 0
	s_setprio 1
	v_mfma_f32_16x16x32_bf16 v[112:115], v[160:163], v[176:179], v[112:115]
	v_mfma_f32_16x16x32_bf16 v[104:107], v[168:171], v[176:179], v[104:107]
	v_mfma_f32_16x16x32_bf16 v[96:99], v[160:163], v[184:187], v[96:99]
	v_mfma_f32_16x16x32_bf16 v[88:91], v[168:171], v[184:187], v[88:91]
	v_mfma_f32_16x16x32_bf16 v[84:87], v[160:163], v[198:201], v[84:87]
	v_mfma_f32_16x16x32_bf16 v[76:79], v[168:171], v[198:201], v[76:79]
	v_mfma_f32_16x16x32_bf16 v[68:71], v[160:163], v[206:209], v[68:71]
	v_mfma_f32_16x16x32_bf16 v[64:67], v[168:171], v[206:209], v[64:67]
	v_mfma_f32_16x16x32_bf16 v[112:115], v[164:167], v[180:183], v[112:115]
	v_mfma_f32_16x16x32_bf16 v[104:107], v[172:175], v[180:183], v[104:107]
	v_mfma_f32_16x16x32_bf16 v[96:99], v[164:167], v[188:191], v[96:99]
	v_mfma_f32_16x16x32_bf16 v[88:91], v[172:175], v[188:191], v[88:91]
	v_mfma_f32_16x16x32_bf16 v[84:87], v[164:167], v[202:205], v[84:87]
	v_mfma_f32_16x16x32_bf16 v[76:79], v[172:175], v[202:205], v[76:79]
	v_mfma_f32_16x16x32_bf16 v[68:71], v[164:167], v[210:213], v[68:71]
	v_mfma_f32_16x16x32_bf16 v[64:67], v[172:175], v[210:213], v[64:67]
	s_setprio 0
	s_barrier
; #define PG8_STAGE(bufoff, gbase, voff) do { _Pragma("unroll") for (int _i = 0; _i < 2; ++_i) \
;         __builtin_amdgcn_global_load_lds((const unsigned*)((const char*)(gbase) + (voff)[_i]), (LAS unsigned*)(lds + (bufoff) + ldsw + _i * 8192), 16, 0, 0); } while (0)
; #define PG8_LDA(dst, b, h) do { _Pragma("unroll") for (int m = 0; m < 4; ++m) _Pragma("unroll") for (int k = 0; k < 2; ++k) dst[m][k] = *(const LAS bf16x8*)(lds + PG8_SA(b, h) + aoff + m * 2048 + k * 1024); } while (0)
; #define PG8_MMA(ai, bj, At, Bt) do { __builtin_amdgcn_s_setprio(1); _Pragma("unroll") for (int m = 0; m < 4; ++m) _Pragma("unroll") for (int n = 0; n < 2; ++n) _Pragma("unroll") for (int k = 0; k < 2; ++k) \
;         acc[ai][bj][m][n] = __builtin_amdgcn_mfma_f32_16x16x32_bf16(Bt[n][k], At[m][k], acc[ai][bj][m][n], 0, 0, 0); __builtin_amdgcn_s_setprio(0); } while (0)
; #define PG8_WAIT_V(n) asm volatile("s_waitcnt vmcnt(" #n ")" ::: "memory")
; #define PG8_WAIT_L(n) asm volatile("s_waitcnt lgkmcnt(" #n ")" ::: "memory")
; #define PG8_BAR __builtin_amdgcn_s_barrier()
; #define PG8_SCHED __builtin_amdgcn_sched_barrier(0)
; template <class Epi, class Sched, bool ALIGN_EPI = false, bool SP2 = false>
; __device__ __forceinline__ void gemm_phase(LAS unsigned char* lds, const Gemm g, const Sched& S, const Epi& E) {
;     ...
;             PG8_LDA(At, 1, 1); PG8_STAGE(PG8_SB(1, 0), b3, voffB); PG8_STAGE(PG8_SB(1, 1), b3 + hstep, voffB); PG8_STAGE(PG8_SA(1, 0), a3, voffA);
;             PG8_WAIT_V(8); PG8_WAIT_L(0); PG8_BAR; PG8_MMA(1, 0, At, B0); PG8_MMA(1, 1, At, B1); PG8_BAR; PG8_SCHED;
	s_add_i32 s28, s91, s2
	s_mov_b32 m0, s28
	ds_read_b128 v[176:179], v143 offset:49152
	ds_read_b128 v[180:183], v143 offset:50176
	ds_read_b128 v[184:187], v143 offset:51200
	ds_read_b128 v[188:191], v143 offset:52224
	ds_read_b128 v[198:201], v143 offset:53248
	ds_read_b128 v[202:205], v143 offset:54272
	ds_read_b128 v[206:209], v143 offset:55296
	ds_read_b128 v[210:213], v143 offset:56320
	global_load_lds_dwordx4 v196, s[98:99]
	s_add_i32 m0, s28, 0x2000
	s_add_u32 s26, s26, 0x100080
	s_addc_u32 s27, s27, 0
	s_add_i32 s28, s58, s2
	global_load_lds_dwordx4 v128, s[98:99]
	s_mov_b32 m0, s28
	s_nop 0
	global_load_lds_dwordx4 v196, s[26:27]
	s_add_i32 m0, s28, 0x2000
	s_nop 0
	global_load_lds_dwordx4 v128, s[26:27]
	s_mov_b32 m0, s30
	s_nop 0
	global_load_lds_dwordx4 v132, s[100:101]
	s_waitcnt vmcnt(7)
	s_waitcnt lgkmcnt(0)
	s_barrier
	s_setprio 1
	s_waitcnt lgkmcnt(0)
	v_mfma_f32_16x16x32_bf16 v[60:63], v[144:147], v[176:179], v[60:63]
	v_mfma_f32_16x16x32_bf16 v[56:59], v[152:155], v[176:179], v[56:59]
	v_mfma_f32_16x16x32_bf16 v[52:55], v[144:147], v[184:187], v[52:55]
	v_mfma_f32_16x16x32_bf16 v[44:47], v[152:155], v[184:187], v[44:47]
	v_mfma_f32_16x16x32_bf16 v[36:39], v[144:147], v[198:201], v[36:39]
	v_mfma_f32_16x16x32_bf16 v[28:31], v[152:155], v[198:201], v[28:31]
	v_mfma_f32_16x16x32_bf16 v[20:23], v[144:147], v[206:209], v[20:23]
	v_mfma_f32_16x16x32_bf16 v[12:15], v[152:155], v[206:209], v[12:15]
	v_mfma_f32_16x16x32_bf16 v[60:63], v[148:151], v[180:183], v[60:63]
	v_mfma_f32_16x16x32_bf16 v[56:59], v[156:159], v[180:183], v[56:59]
	v_mfma_f32_16x16x32_bf16 v[52:55], v[148:151], v[188:191], v[52:55]
	v_mfma_f32_16x16x32_bf16 v[44:47], v[156:159], v[188:191], v[44:47]
	v_mfma_f32_16x16x32_bf16 v[36:39], v[148:151], v[202:205], v[36:39]
	v_mfma_f32_16x16x32_bf16 v[28:31], v[156:159], v[202:205], v[28:31]
	v_mfma_f32_16x16x32_bf16 v[20:23], v[148:151], v[210:213], v[20:23]
	v_mfma_f32_16x16x32_bf16 v[12:15], v[156:159], v[210:213], v[12:15]
	s_setprio 0
	s_setprio 1
	v_mfma_f32_16x16x32_bf16 v[48:51], v[160:163], v[176:179], v[48:51]
	v_mfma_f32_16x16x32_bf16 v[40:43], v[168:171], v[176:179], v[40:43]
	v_mfma_f32_16x16x32_bf16 v[32:35], v[160:163], v[184:187], v[32:35]
	v_mfma_f32_16x16x32_bf16 v[24:27], v[168:171], v[184:187], v[24:27]
	v_mfma_f32_16x16x32_bf16 v[16:19], v[160:163], v[198:201], v[16:19]
	v_mfma_f32_16x16x32_bf16 v[8:11], v[168:171], v[198:201], v[8:11]
	v_mfma_f32_16x16x32_bf16 v[4:7], v[160:163], v[206:209], v[4:7]
	v_mfma_f32_16x16x32_bf16 v[0:3], v[168:171], v[206:209], v[0:3]
	v_mfma_f32_16x16x32_bf16 v[48:51], v[164:167], v[180:183], v[48:51]
	v_mfma_f32_16x16x32_bf16 v[40:43], v[172:175], v[180:183], v[40:43]
	v_mfma_f32_16x16x32_bf16 v[32:35], v[164:167], v[188:191], v[32:35]
	v_mfma_f32_16x16x32_bf16 v[24:27], v[172:175], v[188:191], v[24:27]
	v_mfma_f32_16x16x32_bf16 v[16:19], v[164:167], v[202:205], v[16:19]
	v_mfma_f32_16x16x32_bf16 v[8:11], v[172:175], v[202:205], v[8:11]
	v_mfma_f32_16x16x32_bf16 v[4:7], v[164:167], v[210:213], v[4:7]
	v_mfma_f32_16x16x32_bf16 v[0:3], v[172:175], v[210:213], v[0:3]
	s_setprio 0
	s_barrier
	s_add_i32 s41, s41, 2
	s_add_u32 s24, s24, 0x100
	s_addc_u32 s25, s25, 0
	s_add_u32 s39, s39, 0x100
	s_addc_u32 s40, s40, 0
	s_cmp_gt_u32 s41, 61
	s_cbranch_scc0 .LBB0_510
	s_and_b64 vcc, exec, s[10:11]
	s_cbranch_vccz .LBB0_513
	s_barrier

; #define PG8_STAGE(bufoff, gbase, voff) do { _Pragma("unroll") for (int _i = 0; _i < 2; ++_i) \
;         __builtin_amdgcn_global_load_lds((const unsigned*)((const char*)(gbase) + (voff)[_i]), (LAS unsigned*)(lds + (bufoff) + ldsw + _i * 8192), 16, 0, 0); } while (0)
; #define PG8_LDA(dst, b, h) do { _Pragma("unroll") for (int m = 0; m < 4; ++m) _Pragma("unroll") for (int k = 0; k < 2; ++k) dst[m][k] = *(const LAS bf16x8*)(lds + PG8_SA(b, h) + aoff + m * 2048 + k * 1024); } while (0)
; #define PG8_LDB(dst, b, h) do { _Pragma("unroll") for (int n = 0; n < 2; ++n) _Pragma("unroll") for (int k = 0; k < 2; ++k) dst[n][k] = *(const LAS bf16x8*)(lds + PG8_SB(b, h) + boff + n * 2048 + k * 1024); } while (0)
; #define PG8_MMA(ai, bj, At, Bt) do { __builtin_amdgcn_s_setprio(1); _Pragma("unroll") for (int m = 0; m < 4; ++m) _Pragma("unroll") for (int n = 0; n < 2; ++n) _Pragma("unroll") for (int k = 0; k < 2; ++k) \
;         acc[ai][bj][m][n] = __builtin_amdgcn_mfma_f32_16x16x32_bf16(Bt[n][k], At[m][k], acc[ai][bj][m][n], 0, 0, 0); __builtin_amdgcn_s_setprio(0); } while (0)
; #define PG8_WAIT_V(n) asm volatile("s_waitcnt vmcnt(" #n ")" ::: "memory")
; #define PG8_WAIT_L(n) asm volatile("s_waitcnt lgkmcnt(" #n ")" ::: "memory")
; #define PG8_BAR __builtin_amdgcn_s_barrier()
; #define PG8_SCHED __builtin_amdgcn_sched_barrier(0)
; template <class Epi, class Sched, bool ALIGN_EPI = false, bool SP2 = false>
; __device__ __forceinline__ void gemm_phase(LAS unsigned char* lds, const Gemm g, const Sched& S, const Epi& E) {
;     ...
;             const char* a1 = cA + (size_t)(t + 1) * kstep;
;             const char* a2 = last ? nA : cA + (size_t)(t + 2) * kstep; const char* b2 = last ? nB : cB + (size_t)(t + 2) * kstep;
;             const char* a3 = a2 + kstep; const char* b3 = b2 + kstep;
;             if (last && has_next) S.a_ready(nxt);
;             if constexpr (SP2) {
;             PG8_LDB(B0, 0, 0); PG8_LDB(B1, 0, 1); PG8_SCHED; PG8_LDA(At, 0, 0); PG8_STAGE(PG8_SA(1, 1), a1 + hstep, voffA);
;             PG8_WAIT_V(8); PG8_WAIT_L(0); PG8_BAR; PG8_MMA(0, 0, At, B0); PG8_MMA(0, 1, At, B1); PG8_BAR; PG8_SCHED;
;             PG8_LDA(At, 0, 1); PG8_STAGE(PG8_SB(0, 0), b2, voffB); PG8_STAGE(PG8_SB(0, 1), b2 + hstep, voffB); PG8_STAGE(PG8_SA(0, 0), a2, voffA);
;             PG8_WAIT_V(8); PG8_WAIT_L(0); PG8_BAR; PG8_MMA(1, 0, At, B0); PG8_MMA(1, 1, At, B1); PG8_BAR; PG8_SCHED;
.LBB0_832:
	v_add_u32_e32 v150, s48, v157
	v_add_u32_e32 v154, s90, v157
	ds_read_b128 v[128:131], v150
	ds_read_b128 v[132:135], v150 offset:1024
	ds_read_b128 v[146:149], v150 offset:2048
	ds_read_b128 v[150:153], v150 offset:3072
	ds_read_b128 v[160:163], v154
	ds_read_b128 v[164:167], v154 offset:1024
	ds_read_b128 v[168:171], v154 offset:2048
	ds_read_b128 v[172:175], v154 offset:3072
	s_add_u32 s100, s10, 0xfff00000
	s_addc_u32 s101, s11, -1
	s_add_u32 s34, s10, 0xfff00080
	s_addc_u32 s35, s11, -1
	s_cmp_eq_u32 s62, 60
	s_cselect_b32 s37, s27, s35
	s_cselect_b32 s36, s47, s34
	s_cselect_b32 s35, s25, s59
	s_cselect_b32 s34, s49, s54
	s_add_i32 m0, s3, 0xc000
	ds_read_b128 v[176:179], v159
	ds_read_b128 v[180:183], v159 offset:1024
	ds_read_b128 v[184:187], v159 offset:2048
	ds_read_b128 v[188:191], v159 offset:3072
	ds_read_b128 v[198:201], v159 offset:4096
	ds_read_b128 v[202:205], v159 offset:5120
	ds_read_b128 v[206:209], v159 offset:6144
	ds_read_b128 v[210:213], v159 offset:7168
	s_mov_b32 m0, s42
	s_nop 0
	global_load_lds_dwordx4 v138, s[100:101]
	s_add_i32 m0, s3, 0xc000
	s_nop 0
	global_load_lds_dwordx4 v142, s[10:11]
	s_add_i32 m0, s3, 0xe000
	s_nop 0
	global_load_lds_dwordx4 v144, s[10:11]
	s_waitcnt vmcnt(8)
	s_waitcnt lgkmcnt(0)
	s_barrier
	s_setprio 1
	s_waitcnt lgkmcnt(0)
	v_mfma_f32_16x16x32_bf16 v[124:127], v[128:131], v[176:179], v[124:127]
	v_mfma_f32_16x16x32_bf16 v[120:123], v[146:149], v[176:179], v[120:123]
	v_mfma_f32_16x16x32_bf16 v[108:111], v[128:131], v[184:187], v[108:111]
	v_mfma_f32_16x16x32_bf16 v[104:107], v[146:149], v[184:187], v[104:107]
	v_mfma_f32_16x16x32_bf16 v[92:95], v[128:131], v[198:201], v[92:95]
	v_mfma_f32_16x16x32_bf16 v[88:91], v[146:149], v[198:201], v[88:91]
	v_mfma_f32_16x16x32_bf16 v[76:79], v[128:131], v[206:209], v[76:79]
	v_mfma_f32_16x16x32_bf16 v[72:75], v[146:149], v[206:209], v[72:75]
	v_mfma_f32_16x16x32_bf16 v[124:127], v[132:135], v[180:183], v[124:127]
	v_mfma_f32_16x16x32_bf16 v[120:123], v[150:153], v[180:183], v[120:123]
	v_mfma_f32_16x16x32_bf16 v[108:111], v[132:135], v[188:191], v[108:111]
	v_mfma_f32_16x16x32_bf16 v[104:107], v[150:153], v[188:191], v[104:107]
	v_mfma_f32_16x16x32_bf16 v[92:95], v[132:135], v[202:205], v[92:95]
	v_mfma_f32_16x16x32_bf16 v[88:91], v[150:153], v[202:205], v[88:91]
	v_mfma_f32_16x16x32_bf16 v[76:79], v[132:135], v[210:213], v[76:79]
	v_mfma_f32_16x16x32_bf16 v[72:75], v[150:153], v[210:213], v[72:75]
	s_setprio 0
	s_setprio 1
	v_mfma_f32_16x16x32_bf16 v[116:119], v[160:163], v[176:179], v[116:119]
	v_mfma_f32_16x16x32_bf16 v[112:115], v[168:171], v[176:179], v[112:115]
	v_mfma_f32_16x16x32_bf16 v[100:103], v[160:163], v[184:187], v[100:103]
	v_mfma_f32_16x16x32_bf16 v[96:99], v[168:171], v[184:187], v[96:99]
	v_mfma_f32_16x16x32_bf16 v[84:87], v[160:163], v[198:201], v[84:87]
	v_mfma_f32_16x16x32_bf16 v[80:83], v[168:171], v[198:201], v[80:83]
	v_mfma_f32_16x16x32_bf16 v[68:71], v[160:163], v[206:209], v[68:71]
	v_mfma_f32_16x16x32_bf16 v[64:67], v[168:171], v[206:209], v[64:67]
	v_mfma_f32_16x16x32_bf16 v[116:119], v[164:167], v[180:183], v[116:119]
	v_mfma_f32_16x16x32_bf16 v[112:115], v[172:175], v[180:183], v[112:115]
	v_mfma_f32_16x16x32_bf16 v[100:103], v[164:167], v[188:191], v[100:103]
	v_mfma_f32_16x16x32_bf16 v[96:99], v[172:175], v[188:191], v[96:99]
	v_mfma_f32_16x16x32_bf16 v[84:87], v[164:167], v[202:205], v[84:87]
	v_mfma_f32_16x16x32_bf16 v[80:83], v[172:175], v[202:205], v[80:83]
	v_mfma_f32_16x16x32_bf16 v[68:71], v[164:167], v[210:213], v[68:71]
	v_mfma_f32_16x16x32_bf16 v[64:67], v[172:175], v[210:213], v[64:67]
	s_setprio 0
	s_barrier
	s_add_u32 s98, s34, 0x80
	s_addc_u32 s99, s35, 0
	s_add_u32 s100, s36, 0x80
	s_addc_u32 s101, s37, 0
	s_add_i32 s63, s48, s0
	s_mov_b32 m0, s63
	ds_read_b128 v[176:179], v159 offset:16384
	ds_read_b128 v[180:183], v159 offset:17408
	ds_read_b128 v[184:187], v159 offset:18432
	ds_read_b128 v[188:191], v159 offset:19456
	ds_read_b128 v[198:201], v159 offset:20480
	ds_read_b128 v[202:205], v159 offset:21504
	ds_read_b128 v[206:209], v159 offset:22528
	ds_read_b128 v[210:213], v159 offset:23552
	global_load_lds_dwordx4 v196, s[34:35]
	s_add_i32 m0, s63, 0x2000
	s_add_u32 s64, s34, 0x100000
	s_addc_u32 s65, s35, 0
	s_add_i32 s63, s90, s0
	global_load_lds_dwordx4 v136, s[34:35]
	s_mov_b32 m0, s63
	s_nop 0
	global_load_lds_dwordx4 v196, s[64:65]
	s_add_i32 m0, s63, 0x2000
	s_nop 0
	global_load_lds_dwordx4 v136, s[64:65]
	s_mov_b32 m0, s3
	s_nop 0
	global_load_lds_dwordx4 v140, s[36:37]
	s_waitcnt vmcnt(7)
	s_waitcnt lgkmcnt(0)
	s_barrier
; #define PG8_STAGE(bufoff, gbase, voff) do { _Pragma("unroll") for (int _i = 0; _i < 2; ++_i) \
;         __builtin_amdgcn_global_load_lds((const unsigned*)((const char*)(gbase) + (voff)[_i]), (LAS unsigned*)(lds + (bufoff) + ldsw + _i * 8192), 16, 0, 0); } while (0)
; #define PG8_LDA(dst, b, h) do { _Pragma("unroll") for (int m = 0; m < 4; ++m) _Pragma("unroll") for (int k = 0; k < 2; ++k) dst[m][k] = *(const LAS bf16x8*)(lds + PG8_SA(b, h) + aoff + m * 2048 + k * 1024); } while (0)
; #define PG8_LDB(dst, b, h) do { _Pragma("unroll") for (int n = 0; n < 2; ++n) _Pragma("unroll") for (int k = 0; k < 2; ++k) dst[n][k] = *(const LAS bf16x8*)(lds + PG8_SB(b, h) + boff + n * 2048 + k * 1024); } while (0)
; #define PG8_MMA(ai, bj, At, Bt) do { __builtin_amdgcn_s_setprio(1); _Pragma("unroll") for (int m = 0; m < 4; ++m) _Pragma("unroll") for (int n = 0; n < 2; ++n) _Pragma("unroll") for (int k = 0; k < 2; ++k) \
;         acc[ai][bj][m][n] = __builtin_amdgcn_mfma_f32_16x16x32_bf16(Bt[n][k], At[m][k], acc[ai][bj][m][n], 0, 0, 0); __builtin_amdgcn_s_setprio(0); } while (0)
; #define PG8_WAIT_V(n) asm volatile("s_waitcnt vmcnt(" #n ")" ::: "memory")
; #define PG8_WAIT_L(n) asm volatile("s_waitcnt lgkmcnt(" #n ")" ::: "memory")
; #define PG8_BAR __builtin_amdgcn_s_barrier()
; #define PG8_SCHED __builtin_amdgcn_sched_barrier(0)
; template <class Epi, class Sched, bool ALIGN_EPI = false, bool SP2 = false>
; __device__ __forceinline__ void gemm_phase(LAS unsigned char* lds, const Gemm g, const Sched& S, const Epi& E) {
;     ...
;             PG8_WAIT_V(8); PG8_WAIT_L(0); PG8_BAR; PG8_MMA(0, 0, At, B0); PG8_MMA(0, 1, At, B1); PG8_BAR; PG8_SCHED;
;             PG8_LDA(At, 0, 1); PG8_STAGE(PG8_SB(0, 0), b2, voffB); PG8_STAGE(PG8_SB(0, 1), b2 + hstep, voffB); PG8_STAGE(PG8_SA(0, 0), a2, voffA);
;             PG8_WAIT_V(8); PG8_WAIT_L(0); PG8_BAR; PG8_MMA(1, 0, At, B0); PG8_MMA(1, 1, At, B1); PG8_BAR; PG8_SCHED;
;             PG8_LDB(B0, 1, 0); PG8_LDB(B1, 1, 1); PG8_SCHED; PG8_LDA(At, 1, 0); PG8_STAGE(PG8_SA(0, 1), a2 + hstep, voffA);
;             PG8_WAIT_V(8); PG8_WAIT_L(0); PG8_BAR; PG8_MMA(0, 0, At, B0); PG8_MMA(0, 1, At, B1); PG8_BAR; PG8_SCHED;
;             PG8_LDA(At, 1, 1); PG8_STAGE(PG8_SB(1, 0), b3, voffB); PG8_STAGE(PG8_SB(1, 1), b3 + hstep, voffB); PG8_STAGE(PG8_SA(1, 0), a3, voffA);
	s_setprio 1
	s_waitcnt lgkmcnt(0)
	v_mfma_f32_16x16x32_bf16 v[60:63], v[128:131], v[176:179], v[60:63]
	v_mfma_f32_16x16x32_bf16 v[56:59], v[146:149], v[176:179], v[56:59]
	v_mfma_f32_16x16x32_bf16 v[44:47], v[128:131], v[184:187], v[44:47]
	v_mfma_f32_16x16x32_bf16 v[40:43], v[146:149], v[184:187], v[40:43]
	v_mfma_f32_16x16x32_bf16 v[28:31], v[128:131], v[198:201], v[28:31]
	v_mfma_f32_16x16x32_bf16 v[24:27], v[146:149], v[198:201], v[24:27]
	v_mfma_f32_16x16x32_bf16 v[12:15], v[128:131], v[206:209], v[12:15]
	v_mfma_f32_16x16x32_bf16 v[8:11], v[146:149], v[206:209], v[8:11]
	v_mfma_f32_16x16x32_bf16 v[60:63], v[132:135], v[180:183], v[60:63]
	v_mfma_f32_16x16x32_bf16 v[56:59], v[150:153], v[180:183], v[56:59]
	v_mfma_f32_16x16x32_bf16 v[44:47], v[132:135], v[188:191], v[44:47]
	v_mfma_f32_16x16x32_bf16 v[40:43], v[150:153], v[188:191], v[40:43]
	v_mfma_f32_16x16x32_bf16 v[28:31], v[132:135], v[202:205], v[28:31]
	v_mfma_f32_16x16x32_bf16 v[24:27], v[150:153], v[202:205], v[24:27]
	v_mfma_f32_16x16x32_bf16 v[12:15], v[132:135], v[210:213], v[12:15]
	v_mfma_f32_16x16x32_bf16 v[8:11], v[150:153], v[210:213], v[8:11]
	s_setprio 0
	s_setprio 1
	v_mfma_f32_16x16x32_bf16 v[52:55], v[160:163], v[176:179], v[52:55]
	v_mfma_f32_16x16x32_bf16 v[48:51], v[168:171], v[176:179], v[48:51]
	v_mfma_f32_16x16x32_bf16 v[36:39], v[160:163], v[184:187], v[36:39]
	v_mfma_f32_16x16x32_bf16 v[32:35], v[168:171], v[184:187], v[32:35]
	v_mfma_f32_16x16x32_bf16 v[20:23], v[160:163], v[198:201], v[20:23]
	v_mfma_f32_16x16x32_bf16 v[16:19], v[168:171], v[198:201], v[16:19]
	v_mfma_f32_16x16x32_bf16 v[4:7], v[160:163], v[206:209], v[4:7]
	v_mfma_f32_16x16x32_bf16 v[0:3], v[168:171], v[206:209], v[0:3]
	v_mfma_f32_16x16x32_bf16 v[52:55], v[164:167], v[180:183], v[52:55]
	v_mfma_f32_16x16x32_bf16 v[48:51], v[172:175], v[180:183], v[48:51]
	v_mfma_f32_16x16x32_bf16 v[36:39], v[164:167], v[188:191], v[36:39]
	v_mfma_f32_16x16x32_bf16 v[32:35], v[172:175], v[188:191], v[32:35]
	v_mfma_f32_16x16x32_bf16 v[20:23], v[164:167], v[202:205], v[20:23]
	v_mfma_f32_16x16x32_bf16 v[16:19], v[172:175], v[202:205], v[16:19]
	v_mfma_f32_16x16x32_bf16 v[4:7], v[164:167], v[210:213], v[4:7]
	v_mfma_f32_16x16x32_bf16 v[0:3], v[172:175], v[210:213], v[0:3]
	s_setprio 0
	s_barrier
	v_add_u32_e32 v150, s91, v157
	v_add_u32_e32 v172, s58, v157
	ds_read_b128 v[128:131], v150
	ds_read_b128 v[132:135], v150 offset:1024
	ds_read_b128 v[146:149], v150 offset:2048
	ds_read_b128 v[150:153], v150 offset:3072
	ds_read_b128 v[160:163], v172
	ds_read_b128 v[164:167], v172 offset:1024
	ds_read_b128 v[168:171], v172 offset:2048
	ds_read_b128 v[172:175], v172 offset:3072
	s_mov_b32 m0, s17
	s_nop 0
	global_load_lds_dwordx4 v138, s[36:37]
	s_add_u32 s36, s36, 0x100000
	s_addc_u32 s37, s37, 0
	s_mov_b32 m0, s38
	ds_read_b128 v[176:179], v159 offset:32768
	ds_read_b128 v[180:183], v159 offset:33792
	ds_read_b128 v[184:187], v159 offset:34816
	ds_read_b128 v[188:191], v159 offset:35840
	ds_read_b128 v[198:201], v159 offset:36864
	ds_read_b128 v[202:205], v159 offset:37888
	ds_read_b128 v[206:209], v159 offset:38912
	ds_read_b128 v[210:213], v159 offset:39936
	global_load_lds_dwordx4 v140, s[36:37]
	s_mov_b32 m0, s39
	s_nop 0
	global_load_lds_dwordx4 v138, s[36:37]
	s_waitcnt vmcnt(8)
	s_waitcnt lgkmcnt(0)
	s_barrier
	s_setprio 1
	s_waitcnt lgkmcnt(0)
	v_mfma_f32_16x16x32_bf16 v[124:127], v[128:131], v[176:179], v[124:127]
	v_mfma_f32_16x16x32_bf16 v[120:123], v[146:149], v[176:179], v[120:123]
	v_mfma_f32_16x16x32_bf16 v[108:111], v[128:131], v[184:187], v[108:111]
	v_mfma_f32_16x16x32_bf16 v[104:107], v[146:149], v[184:187], v[104:107]
	v_mfma_f32_16x16x32_bf16 v[92:95], v[128:131], v[198:201], v[92:95]
	v_mfma_f32_16x16x32_bf16 v[88:91], v[146:149], v[198:201], v[88:91]
	v_mfma_f32_16x16x32_bf16 v[76:79], v[128:131], v[206:209], v[76:79]
	v_mfma_f32_16x16x32_bf16 v[72:75], v[146:149], v[206:209], v[72:75]
	v_mfma_f32_16x16x32_bf16 v[124:127], v[132:135], v[180:183], v[124:127]
	v_mfma_f32_16x16x32_bf16 v[120:123], v[150:153], v[180:183], v[120:123]
	v_mfma_f32_16x16x32_bf16 v[108:111], v[132:135], v[188:191], v[108:111]
	v_mfma_f32_16x16x32_bf16 v[104:107], v[150:153], v[188:191], v[104:107]
	v_mfma_f32_16x16x32_bf16 v[92:95], v[132:135], v[202:205], v[92:95]
	v_mfma_f32_16x16x32_bf16 v[88:91], v[150:153], v[202:205], v[88:91]
	v_mfma_f32_16x16x32_bf16 v[76:79], v[132:135], v[210:213], v[76:79]
	v_mfma_f32_16x16x32_bf16 v[72:75], v[150:153], v[210:213], v[72:75]
	s_setprio 0
	s_setprio 1
	v_mfma_f32_16x16x32_bf16 v[116:119], v[160:163], v[176:179], v[116:119]
	v_mfma_f32_16x16x32_bf16 v[112:115], v[168:171], v[176:179], v[112:115]
	v_mfma_f32_16x16x32_bf16 v[100:103], v[160:163], v[184:187], v[100:103]
	v_mfma_f32_16x16x32_bf16 v[96:99], v[168:171], v[184:187], v[96:99]
	v_mfma_f32_16x16x32_bf16 v[84:87], v[160:163], v[198:201], v[84:87]
	v_mfma_f32_16x16x32_bf16 v[80:83], v[168:171], v[198:201], v[80:83]
	v_mfma_f32_16x16x32_bf16 v[68:71], v[160:163], v[206:209], v[68:71]
	v_mfma_f32_16x16x32_bf16 v[64:67], v[168:171], v[206:209], v[64:67]
	v_mfma_f32_16x16x32_bf16 v[116:119], v[164:167], v[180:183], v[116:119]
	v_mfma_f32_16x16x32_bf16 v[112:115], v[172:175], v[180:183], v[112:115]
	v_mfma_f32_16x16x32_bf16 v[100:103], v[164:167], v[188:191], v[100:103]
	v_mfma_f32_16x16x32_bf16 v[96:99], v[172:175], v[188:191], v[96:99]
	v_mfma_f32_16x16x32_bf16 v[84:87], v[164:167], v[202:205], v[84:87]
	v_mfma_f32_16x16x32_bf16 v[80:83], v[172:175], v[202:205], v[80:83]
	v_mfma_f32_16x16x32_bf16 v[68:71], v[164:167], v[210:213], v[68:71]
	v_mfma_f32_16x16x32_bf16 v[64:67], v[172:175], v[210:213], v[64:67]
	s_setprio 0
	s_barrier
; #define PG8_STAGE(bufoff, gbase, voff) do { _Pragma("unroll") for (int _i = 0; _i < 2; ++_i) \
;         __builtin_amdgcn_global_load_lds((const unsigned*)((const char*)(gbase) + (voff)[_i]), (LAS unsigned*)(lds + (bufoff) + ldsw + _i * 8192), 16, 0, 0); } while (0)
; #define PG8_LDA(dst, b, h) do { _Pragma("unroll") for (int m = 0; m < 4; ++m) _Pragma("unroll") for (int k = 0; k < 2; ++k) dst[m][k] = *(const LAS bf16x8*)(lds + PG8_SA(b, h) + aoff + m * 2048 + k * 1024); } while (0)
; #define PG8_MMA(ai, bj, At, Bt) do { __builtin_amdgcn_s_setprio(1); _Pragma("unroll") for (int m = 0; m < 4; ++m) _Pragma("unroll") for (int n = 0; n < 2; ++n) _Pragma("unroll") for (int k = 0; k < 2; ++k) \
;         acc[ai][bj][m][n] = __builtin_amdgcn_mfma_f32_16x16x32_bf16(Bt[n][k], At[m][k], acc[ai][bj][m][n], 0, 0, 0); __builtin_amdgcn_s_setprio(0); } while (0)
; #define PG8_WAIT_V(n) asm volatile("s_waitcnt vmcnt(" #n ")" ::: "memory")
; #define PG8_WAIT_L(n) asm volatile("s_waitcnt lgkmcnt(" #n ")" ::: "memory")
; #define PG8_BAR __builtin_amdgcn_s_barrier()
; #define PG8_SCHED __builtin_amdgcn_sched_barrier(0)
; template <class Epi, class Sched, bool ALIGN_EPI = false, bool SP2 = false>
; __device__ __forceinline__ void gemm_phase(LAS unsigned char* lds, const Gemm g, const Sched& S, const Epi& E) {
;     ...
;             PG8_WAIT_V(8); PG8_WAIT_L(0); PG8_BAR; PG8_MMA(0, 0, At, B0); PG8_MMA(0, 1, At, B1); PG8_BAR; PG8_SCHED;
;             PG8_LDA(At, 1, 1); PG8_STAGE(PG8_SB(1, 0), b3, voffB); PG8_STAGE(PG8_SB(1, 1), b3 + hstep, voffB); PG8_STAGE(PG8_SA(1, 0), a3, voffA);
;             PG8_WAIT_V(8); PG8_WAIT_L(0); PG8_BAR; PG8_MMA(1, 0, At, B0); PG8_MMA(1, 1, At, B1); PG8_BAR; PG8_SCHED;
;     ...
;         if constexpr (ALIGN_EPI) { if (wr == 0) PG8_BAR; }
	s_add_i32 s36, s91, s0
	s_mov_b32 m0, s36
	ds_read_b128 v[176:179], v159 offset:49152
	ds_read_b128 v[180:183], v159 offset:50176
	ds_read_b128 v[184:187], v159 offset:51200
	ds_read_b128 v[188:191], v159 offset:52224
	ds_read_b128 v[198:201], v159 offset:53248
	ds_read_b128 v[202:205], v159 offset:54272
	ds_read_b128 v[206:209], v159 offset:55296
	ds_read_b128 v[210:213], v159 offset:56320
	global_load_lds_dwordx4 v196, s[98:99]
	s_add_i32 m0, s36, 0x2000
	s_add_u32 s34, s34, 0x100080
	s_addc_u32 s35, s35, 0
	s_add_i32 s36, s58, s0
	global_load_lds_dwordx4 v136, s[98:99]
	s_mov_b32 m0, s36
	s_nop 0
	global_load_lds_dwordx4 v196, s[34:35]
	s_add_i32 m0, s36, 0x2000
	s_nop 0
	global_load_lds_dwordx4 v136, s[34:35]
	s_mov_b32 m0, s41
	s_nop 0
	global_load_lds_dwordx4 v140, s[100:101]
	s_waitcnt vmcnt(7)
	s_waitcnt lgkmcnt(0)
	s_barrier
	s_setprio 1
	s_waitcnt lgkmcnt(0)
	v_mfma_f32_16x16x32_bf16 v[60:63], v[128:131], v[176:179], v[60:63]
	v_mfma_f32_16x16x32_bf16 v[56:59], v[146:149], v[176:179], v[56:59]
	v_mfma_f32_16x16x32_bf16 v[44:47], v[128:131], v[184:187], v[44:47]
	v_mfma_f32_16x16x32_bf16 v[40:43], v[146:149], v[184:187], v[40:43]
	v_mfma_f32_16x16x32_bf16 v[28:31], v[128:131], v[198:201], v[28:31]
	v_mfma_f32_16x16x32_bf16 v[24:27], v[146:149], v[198:201], v[24:27]
	v_mfma_f32_16x16x32_bf16 v[12:15], v[128:131], v[206:209], v[12:15]
	v_mfma_f32_16x16x32_bf16 v[8:11], v[146:149], v[206:209], v[8:11]
	v_mfma_f32_16x16x32_bf16 v[60:63], v[132:135], v[180:183], v[60:63]
	v_mfma_f32_16x16x32_bf16 v[56:59], v[150:153], v[180:183], v[56:59]
	v_mfma_f32_16x16x32_bf16 v[44:47], v[132:135], v[188:191], v[44:47]
	v_mfma_f32_16x16x32_bf16 v[40:43], v[150:153], v[188:191], v[40:43]
	v_mfma_f32_16x16x32_bf16 v[28:31], v[132:135], v[202:205], v[28:31]
	v_mfma_f32_16x16x32_bf16 v[24:27], v[150:153], v[202:205], v[24:27]
	v_mfma_f32_16x16x32_bf16 v[12:15], v[132:135], v[210:213], v[12:15]
	v_mfma_f32_16x16x32_bf16 v[8:11], v[150:153], v[210:213], v[8:11]
	s_setprio 0
	s_setprio 1
	v_mfma_f32_16x16x32_bf16 v[52:55], v[160:163], v[176:179], v[52:55]
	v_mfma_f32_16x16x32_bf16 v[48:51], v[168:171], v[176:179], v[48:51]
	v_mfma_f32_16x16x32_bf16 v[36:39], v[160:163], v[184:187], v[36:39]
	v_mfma_f32_16x16x32_bf16 v[32:35], v[168:171], v[184:187], v[32:35]
	v_mfma_f32_16x16x32_bf16 v[20:23], v[160:163], v[198:201], v[20:23]
	v_mfma_f32_16x16x32_bf16 v[16:19], v[168:171], v[198:201], v[16:19]
	v_mfma_f32_16x16x32_bf16 v[4:7], v[160:163], v[206:209], v[4:7]
	v_mfma_f32_16x16x32_bf16 v[0:3], v[168:171], v[206:209], v[0:3]
	v_mfma_f32_16x16x32_bf16 v[52:55], v[164:167], v[180:183], v[52:55]
	v_mfma_f32_16x16x32_bf16 v[48:51], v[172:175], v[180:183], v[48:51]
	v_mfma_f32_16x16x32_bf16 v[36:39], v[164:167], v[188:191], v[36:39]
	v_mfma_f32_16x16x32_bf16 v[32:35], v[172:175], v[188:191], v[32:35]
	v_mfma_f32_16x16x32_bf16 v[20:23], v[164:167], v[202:205], v[20:23]
	v_mfma_f32_16x16x32_bf16 v[16:19], v[172:175], v[202:205], v[16:19]
	v_mfma_f32_16x16x32_bf16 v[4:7], v[164:167], v[210:213], v[4:7]
	v_mfma_f32_16x16x32_bf16 v[0:3], v[172:175], v[210:213], v[0:3]
	s_setprio 0
	s_barrier
	s_add_i32 s62, s62, 2
	s_add_u32 s10, s10, 0x100
	s_addc_u32 s11, s11, 0
	s_add_u32 s54, s54, 0x100
	s_addc_u32 s59, s59, 0
	s_cmp_gt_u32 s62, 61
	s_cbranch_scc0 .LBB0_832
	s_and_b64 vcc, exec, s[20:21]
	s_cbranch_vccz .LBB0_835
	s_barrier
